# stack+GEMM-MMA-blocks-drop-back-to-back-setprio-0-1-flip
# baseline (speedup 1.0000x reference)
; #define PG8_STAGE(bufoff, gbase, voff) do { _Pragma("unroll") for (int _i = 0; _i < 2; ++_i) \
;         __builtin_amdgcn_global_load_lds((const unsigned*)((const char*)(gbase) + (voff)[_i]), (PG8_LAS unsigned*)(lds + (bufoff) + ldsw + _i * 8192), 16, 0, 0); } while (0)
; #define PG8_LDA(dst, b, h) do { _Pragma("unroll") for (int m = 0; m < 4; ++m) _Pragma("unroll") for (int k = 0; k < 2; ++k) dst[m][k] = *(const PG8_LAS bf16x8*)(lds + PG8_SA(b, h) + aoff + m * 2048 + k * 1024); } while (0)
; #define PG8_LDB(dst, b, h) do { _Pragma("unroll") for (int n = 0; n < 2; ++n) _Pragma("unroll") for (int k = 0; k < 2; ++k) dst[n][k] = *(const PG8_LAS bf16x8*)(lds + PG8_SB(b, h) + boff + n * 2048 + k * 1024); } while (0)
; #define PG8_MMA(ai, bj, At, Bt) do { __builtin_amdgcn_s_setprio(1); _Pragma("unroll") for (int m = 0; m < 4; ++m) _Pragma("unroll") for (int n = 0; n < 2; ++n) _Pragma("unroll") for (int k = 0; k < 2; ++k) \
;         acc[ai][bj][m][n] = __builtin_amdgcn_mfma_f32_16x16x32_bf16(Bt[n][k], At[m][k], acc[ai][bj][m][n], 0, 0, 0); __builtin_amdgcn_s_setprio(0); } while (0)
; #define PG8_WAIT_V(n) asm volatile("s_waitcnt vmcnt(" #n ")" ::: "memory")
; #define PG8_WAIT_L(n) asm volatile("s_waitcnt lgkmcnt(" #n ")" ::: "memory")
; template <class Epi, class Sched, bool ALIGN_EPI = false, bool SP2 = false>
; __device__ __forceinline__ void gemm_phase(PG8_LAS unsigned char* lds, const Gemm g, const Sched& S, const Epi& E) {
;     ...
;             const bool last = (t == nt - 2);
;             const char* a1 = cA + (size_t)(t + 1) * kstep;
;             const char* a2 = last ? nA : cA + (size_t)(t + 2) * kstep; const char* b2 = last ? nB : cB + (size_t)(t + 2) * kstep;
;             const char* a3 = a2 + kstep; const char* b3 = b2 + kstep;
;             if (last && has_next) S.a_ready(nxt);
;             if constexpr (SP2) {
;             PG8_LDB(B0, 0, 0); PG8_LDB(B1, 0, 1); PG8_SCHED; PG8_LDA(At, 0, 0); PG8_STAGE(PG8_SA(1, 1), a1 + hstep, voffA);
;             PG8_WAIT_V(8); PG8_WAIT_L(0); PG8_BAR; PG8_MMA(0, 0, At, B0); PG8_MMA(0, 1, At, B1); PG8_BAR; PG8_SCHED;
;             PG8_LDA(At, 0, 1); PG8_STAGE(PG8_SB(0, 0), b2, voffB); PG8_STAGE(PG8_SB(0, 1), b2 + hstep, voffB); PG8_STAGE(PG8_SA(0, 0), a2, voffA);
;             PG8_WAIT_V(8); PG8_WAIT_L(0); PG8_BAR; PG8_MMA(1, 0, At, B0); PG8_MMA(1, 1, At, B1); PG8_BAR; PG8_SCHED;
.LBB0_188:
	s_add_u32 s52, s42, 0xfffc0080
	s_addc_u32 s53, s43, -1
	s_add_i32 s70, 0, 0x10000
	s_cmp_eq_u32 s91, 12
	s_cselect_b32 s55, s6, s53
	s_cselect_b32 s54, s7, s52
	s_cselect_b32 s53, s45, s90
	s_cselect_b32 s52, s47, s89
	s_add_i32 s71, 0, 0x14000
	v_add_u32_e32 v158, s70, v147
	v_add_u32_e32 v162, s71, v147
	ds_read_b128 v[142:145], v158
	ds_read_b128 v[150:153], v158 offset:1024
	ds_read_b128 v[154:157], v158 offset:2048
	ds_read_b128 v[158:161], v158 offset:3072
	ds_read_b128 v[180:183], v162
	ds_read_b128 v[184:187], v162 offset:1024
	ds_read_b128 v[188:191], v162 offset:2048
	ds_read_b128 v[192:195], v162 offset:3072
	v_lshl_add_u64 v[162:163], s[42:43], 0, v[138:139]
	s_add_i32 m0, s57, 0xc000
	ds_read_b128 v[208:211], v149
	ds_read_b128 v[212:215], v149 offset:1024
	ds_read_b128 v[216:219], v149 offset:2048
	ds_read_b128 v[224:227], v149 offset:3072
	ds_read_b128 v[228:231], v149 offset:4096
	ds_read_b128 v[232:235], v149 offset:5120
	ds_read_b128 v[236:239], v149 offset:6144
	ds_read_b128 v[240:243], v149 offset:7168
	global_load_lds_dwordx4 v[162:163], off
	v_lshl_add_u64 v[162:163], s[42:43], 0, v[140:141]
	s_add_i32 m0, s57, 0xe000
	s_nop 0
	global_load_lds_dwordx4 v[162:163], off
	s_waitcnt vmcnt(8)
	s_waitcnt lgkmcnt(0)
	s_barrier
	s_setprio 1
	s_waitcnt lgkmcnt(0)
	v_mfma_f32_16x16x32_bf16 v[128:131], v[142:145], v[208:211], v[128:131]
	v_mfma_f32_16x16x32_bf16 v[124:127], v[154:157], v[208:211], v[124:127]
	v_mfma_f32_16x16x32_bf16 v[116:119], v[142:145], v[216:219], v[116:119]
	v_mfma_f32_16x16x32_bf16 v[108:111], v[154:157], v[216:219], v[108:111]
	v_mfma_f32_16x16x32_bf16 v[100:103], v[142:145], v[228:231], v[100:103]
	v_mfma_f32_16x16x32_bf16 v[92:95], v[154:157], v[228:231], v[92:95]
	v_mfma_f32_16x16x32_bf16 v[84:87], v[142:145], v[236:239], v[84:87]
	v_mfma_f32_16x16x32_bf16 v[76:79], v[154:157], v[236:239], v[76:79]
	v_mfma_f32_16x16x32_bf16 v[128:131], v[150:153], v[212:215], v[128:131]
	v_mfma_f32_16x16x32_bf16 v[124:127], v[158:161], v[212:215], v[124:127]
	v_mfma_f32_16x16x32_bf16 v[116:119], v[150:153], v[224:227], v[116:119]
	v_mfma_f32_16x16x32_bf16 v[108:111], v[158:161], v[224:227], v[108:111]
	v_mfma_f32_16x16x32_bf16 v[100:103], v[150:153], v[232:235], v[100:103]
	v_mfma_f32_16x16x32_bf16 v[92:95], v[158:161], v[232:235], v[92:95]
	v_mfma_f32_16x16x32_bf16 v[84:87], v[150:153], v[240:243], v[84:87]
	v_mfma_f32_16x16x32_bf16 v[76:79], v[158:161], v[240:243], v[76:79]
	v_mfma_f32_16x16x32_bf16 v[120:123], v[180:183], v[208:211], v[120:123]
	v_mfma_f32_16x16x32_bf16 v[112:115], v[188:191], v[208:211], v[112:115]
	v_mfma_f32_16x16x32_bf16 v[104:107], v[180:183], v[216:219], v[104:107]
	v_mfma_f32_16x16x32_bf16 v[96:99], v[188:191], v[216:219], v[96:99]
	v_mfma_f32_16x16x32_bf16 v[88:91], v[180:183], v[228:231], v[88:91]
	v_mfma_f32_16x16x32_bf16 v[80:83], v[188:191], v[228:231], v[80:83]
	v_mfma_f32_16x16x32_bf16 v[72:75], v[180:183], v[236:239], v[72:75]
	v_mfma_f32_16x16x32_bf16 v[68:71], v[188:191], v[236:239], v[68:71]
	v_mfma_f32_16x16x32_bf16 v[120:123], v[184:187], v[212:215], v[120:123]
	v_mfma_f32_16x16x32_bf16 v[112:115], v[192:195], v[212:215], v[112:115]
	v_mfma_f32_16x16x32_bf16 v[104:107], v[184:187], v[224:227], v[104:107]
	v_mfma_f32_16x16x32_bf16 v[96:99], v[192:195], v[224:227], v[96:99]
	v_mfma_f32_16x16x32_bf16 v[88:91], v[184:187], v[232:235], v[88:91]
	v_mfma_f32_16x16x32_bf16 v[80:83], v[192:195], v[232:235], v[80:83]
	v_mfma_f32_16x16x32_bf16 v[72:75], v[184:187], v[240:243], v[72:75]
	v_mfma_f32_16x16x32_bf16 v[68:71], v[192:195], v[240:243], v[68:71]
	s_setprio 0
	s_barrier
	s_add_i32 s70, s70, s56
	v_lshl_add_u64 v[162:163], s[52:53], 0, v[2:3]
	s_mov_b32 m0, s70
	ds_read_b128 v[208:211], v149 offset:16384
	ds_read_b128 v[212:215], v149 offset:17408
	ds_read_b128 v[216:219], v149 offset:18432
	ds_read_b128 v[224:227], v149 offset:19456
	ds_read_b128 v[228:231], v149 offset:20480
	ds_read_b128 v[232:235], v149 offset:21504
	ds_read_b128 v[236:239], v149 offset:22528
	ds_read_b128 v[240:243], v149 offset:23552
	global_load_lds_dwordx4 v[162:163], off
	s_add_i32 m0, s70, 0x2000
	s_add_u32 vcc_lo, s52, 0x40000
	v_lshl_add_u64 v[196:197], s[52:53], 0, v[132:133]
	s_addc_u32 vcc_hi, s53, 0
	s_add_i32 s70, s71, s56
	global_load_lds_dwordx4 v[196:197], off
	v_lshl_add_u64 v[244:245], vcc, 0, v[2:3]
	s_mov_b32 m0, s70
	v_lshl_add_u64 v[246:247], s[54:55], 0, v[134:135]
	global_load_lds_dwordx4 v[244:245], off
	v_lshl_add_u64 v[244:245], vcc, 0, v[132:133]
	s_add_i32 m0, s70, 0x2000
	s_nop 0
	global_load_lds_dwordx4 v[244:245], off
	v_lshl_add_u64 v[244:245], s[54:55], 0, v[136:137]
	s_mov_b32 m0, s57
	s_nop 0
	global_load_lds_dwordx4 v[244:245], off
	s_mov_b32 m0, s78
	s_nop 0
	global_load_lds_dwordx4 v[246:247], off
	s_waitcnt vmcnt(8)
	s_waitcnt lgkmcnt(0)
	s_barrier
; #define PG8_STAGE(bufoff, gbase, voff) do { _Pragma("unroll") for (int _i = 0; _i < 2; ++_i) \
;         __builtin_amdgcn_global_load_lds((const unsigned*)((const char*)(gbase) + (voff)[_i]), (PG8_LAS unsigned*)(lds + (bufoff) + ldsw + _i * 8192), 16, 0, 0); } while (0)
; #define PG8_LDA(dst, b, h) do { _Pragma("unroll") for (int m = 0; m < 4; ++m) _Pragma("unroll") for (int k = 0; k < 2; ++k) dst[m][k] = *(const PG8_LAS bf16x8*)(lds + PG8_SA(b, h) + aoff + m * 2048 + k * 1024); } while (0)
; #define PG8_LDB(dst, b, h) do { _Pragma("unroll") for (int n = 0; n < 2; ++n) _Pragma("unroll") for (int k = 0; k < 2; ++k) dst[n][k] = *(const PG8_LAS bf16x8*)(lds + PG8_SB(b, h) + boff + n * 2048 + k * 1024); } while (0)
; #define PG8_MMA(ai, bj, At, Bt) do { __builtin_amdgcn_s_setprio(1); _Pragma("unroll") for (int m = 0; m < 4; ++m) _Pragma("unroll") for (int n = 0; n < 2; ++n) _Pragma("unroll") for (int k = 0; k < 2; ++k) \
;         acc[ai][bj][m][n] = __builtin_amdgcn_mfma_f32_16x16x32_bf16(Bt[n][k], At[m][k], acc[ai][bj][m][n], 0, 0, 0); __builtin_amdgcn_s_setprio(0); } while (0)
; #define PG8_WAIT_V(n) asm volatile("s_waitcnt vmcnt(" #n ")" ::: "memory")
; #define PG8_WAIT_L(n) asm volatile("s_waitcnt lgkmcnt(" #n ")" ::: "memory")
; #define PG8_BAR __builtin_amdgcn_s_barrier()
; #define PG8_SCHED __builtin_amdgcn_sched_barrier(0)
; template <class Epi, class Sched, bool ALIGN_EPI = false, bool SP2 = false>
; __device__ __forceinline__ void gemm_phase(PG8_LAS unsigned char* lds, const Gemm g, const Sched& S, const Epi& E) {
;     ...
;             PG8_WAIT_V(8); PG8_WAIT_L(0); PG8_BAR; PG8_MMA(1, 0, At, B0); PG8_MMA(1, 1, At, B1); PG8_BAR; PG8_SCHED;
;             PG8_LDB(B0, 1, 0); PG8_LDB(B1, 1, 1); PG8_SCHED; PG8_LDA(At, 1, 0); PG8_STAGE(PG8_SA(0, 1), a2 + hstep, voffA);
;             PG8_WAIT_V(8); PG8_WAIT_L(0); PG8_BAR; PG8_MMA(0, 0, At, B0); PG8_MMA(0, 1, At, B1); PG8_BAR; PG8_SCHED;
	s_setprio 1
	s_waitcnt lgkmcnt(0)
	v_mfma_f32_16x16x32_bf16 v[64:67], v[142:145], v[208:211], v[64:67]
	v_mfma_f32_16x16x32_bf16 v[60:63], v[154:157], v[208:211], v[60:63]
	v_mfma_f32_16x16x32_bf16 v[52:55], v[142:145], v[216:219], v[52:55]
	v_mfma_f32_16x16x32_bf16 v[44:47], v[154:157], v[216:219], v[44:47]
	v_mfma_f32_16x16x32_bf16 v[36:39], v[142:145], v[228:231], v[36:39]
	v_mfma_f32_16x16x32_bf16 v[28:31], v[154:157], v[228:231], v[28:31]
	v_mfma_f32_16x16x32_bf16 v[20:23], v[142:145], v[236:239], v[20:23]
	v_mfma_f32_16x16x32_bf16 v[12:15], v[154:157], v[236:239], v[12:15]
	v_mfma_f32_16x16x32_bf16 v[64:67], v[150:153], v[212:215], v[64:67]
	v_mfma_f32_16x16x32_bf16 v[60:63], v[158:161], v[212:215], v[60:63]
	v_mfma_f32_16x16x32_bf16 v[52:55], v[150:153], v[224:227], v[52:55]
	v_mfma_f32_16x16x32_bf16 v[44:47], v[158:161], v[224:227], v[44:47]
	v_mfma_f32_16x16x32_bf16 v[36:39], v[150:153], v[232:235], v[36:39]
	v_mfma_f32_16x16x32_bf16 v[28:31], v[158:161], v[232:235], v[28:31]
	v_mfma_f32_16x16x32_bf16 v[20:23], v[150:153], v[240:243], v[20:23]
	v_mfma_f32_16x16x32_bf16 v[12:15], v[158:161], v[240:243], v[12:15]
	v_mfma_f32_16x16x32_bf16 v[56:59], v[180:183], v[208:211], v[56:59]
	v_mfma_f32_16x16x32_bf16 v[48:51], v[188:191], v[208:211], v[48:51]
	v_mfma_f32_16x16x32_bf16 v[40:43], v[180:183], v[216:219], v[40:43]
	v_mfma_f32_16x16x32_bf16 v[32:35], v[188:191], v[216:219], v[32:35]
	v_mfma_f32_16x16x32_bf16 v[24:27], v[180:183], v[228:231], v[24:27]
	v_mfma_f32_16x16x32_bf16 v[16:19], v[188:191], v[228:231], v[16:19]
	v_mfma_f32_16x16x32_bf16 v[8:11], v[180:183], v[236:239], v[8:11]
	v_mfma_f32_16x16x32_bf16 v[4:7], v[188:191], v[236:239], v[4:7]
	v_mfma_f32_16x16x32_bf16 v[56:59], v[184:187], v[212:215], v[56:59]
	v_mfma_f32_16x16x32_bf16 v[48:51], v[192:195], v[212:215], v[48:51]
	v_mfma_f32_16x16x32_bf16 v[40:43], v[184:187], v[224:227], v[40:43]
	v_mfma_f32_16x16x32_bf16 v[32:35], v[192:195], v[224:227], v[32:35]
	v_mfma_f32_16x16x32_bf16 v[24:27], v[184:187], v[232:235], v[24:27]
	v_mfma_f32_16x16x32_bf16 v[16:19], v[192:195], v[232:235], v[16:19]
	v_mfma_f32_16x16x32_bf16 v[8:11], v[184:187], v[240:243], v[8:11]
	v_mfma_f32_16x16x32_bf16 v[4:7], v[192:195], v[240:243], v[4:7]
	s_setprio 0
	s_barrier
	s_add_i32 s70, 0, 0x18000
	s_add_i32 s71, 0, 0x1c000
	v_add_u32_e32 v158, s70, v147
	v_add_u32_e32 v167, s71, v147
	ds_read_b128 v[142:145], v158
	ds_read_b128 v[150:153], v158 offset:1024
	ds_read_b128 v[154:157], v158 offset:2048
	ds_read_b128 v[158:161], v158 offset:3072
	ds_read_b128 v[180:183], v167
	ds_read_b128 v[184:187], v167 offset:1024
	ds_read_b128 v[188:191], v167 offset:2048
	ds_read_b128 v[192:195], v167 offset:3072
	s_add_u32 s54, s54, 0x40000
	s_addc_u32 s55, s55, 0
	s_mov_b32 m0, s79
	v_lshl_add_u64 v[248:249], s[54:55], 0, v[136:137]
	ds_read_b128 v[208:211], v149 offset:32768
	ds_read_b128 v[212:215], v149 offset:33792
	ds_read_b128 v[216:219], v149 offset:34816
	ds_read_b128 v[224:227], v149 offset:35840
	ds_read_b128 v[228:231], v149 offset:36864
	ds_read_b128 v[232:235], v149 offset:37888
	ds_read_b128 v[236:239], v149 offset:38912
	ds_read_b128 v[240:243], v149 offset:39936
	global_load_lds_dwordx4 v[248:249], off
	v_lshl_add_u64 v[248:249], s[54:55], 0, v[134:135]
	s_mov_b32 m0, s80
	s_nop 0
	global_load_lds_dwordx4 v[248:249], off
	s_waitcnt vmcnt(8)
	s_waitcnt lgkmcnt(0)
	s_barrier
	s_setprio 1
	s_waitcnt lgkmcnt(0)
	v_mfma_f32_16x16x32_bf16 v[128:131], v[142:145], v[208:211], v[128:131]
	v_mfma_f32_16x16x32_bf16 v[124:127], v[154:157], v[208:211], v[124:127]
	v_mfma_f32_16x16x32_bf16 v[116:119], v[142:145], v[216:219], v[116:119]
	v_mfma_f32_16x16x32_bf16 v[108:111], v[154:157], v[216:219], v[108:111]
	v_mfma_f32_16x16x32_bf16 v[100:103], v[142:145], v[228:231], v[100:103]
	v_mfma_f32_16x16x32_bf16 v[92:95], v[154:157], v[228:231], v[92:95]
	v_mfma_f32_16x16x32_bf16 v[84:87], v[142:145], v[236:239], v[84:87]
	v_mfma_f32_16x16x32_bf16 v[76:79], v[154:157], v[236:239], v[76:79]
	v_mfma_f32_16x16x32_bf16 v[128:131], v[150:153], v[212:215], v[128:131]
	v_mfma_f32_16x16x32_bf16 v[124:127], v[158:161], v[212:215], v[124:127]
	v_mfma_f32_16x16x32_bf16 v[116:119], v[150:153], v[224:227], v[116:119]
	v_mfma_f32_16x16x32_bf16 v[108:111], v[158:161], v[224:227], v[108:111]
	v_mfma_f32_16x16x32_bf16 v[100:103], v[150:153], v[232:235], v[100:103]
	v_mfma_f32_16x16x32_bf16 v[92:95], v[158:161], v[232:235], v[92:95]
	v_mfma_f32_16x16x32_bf16 v[84:87], v[150:153], v[240:243], v[84:87]
	v_mfma_f32_16x16x32_bf16 v[76:79], v[158:161], v[240:243], v[76:79]
	v_mfma_f32_16x16x32_bf16 v[120:123], v[180:183], v[208:211], v[120:123]
	v_mfma_f32_16x16x32_bf16 v[112:115], v[188:191], v[208:211], v[112:115]
	v_mfma_f32_16x16x32_bf16 v[104:107], v[180:183], v[216:219], v[104:107]
	v_mfma_f32_16x16x32_bf16 v[96:99], v[188:191], v[216:219], v[96:99]
	v_mfma_f32_16x16x32_bf16 v[88:91], v[180:183], v[228:231], v[88:91]
	v_mfma_f32_16x16x32_bf16 v[80:83], v[188:191], v[228:231], v[80:83]
	v_mfma_f32_16x16x32_bf16 v[72:75], v[180:183], v[236:239], v[72:75]
	v_mfma_f32_16x16x32_bf16 v[68:71], v[188:191], v[236:239], v[68:71]
	v_mfma_f32_16x16x32_bf16 v[120:123], v[184:187], v[212:215], v[120:123]
	v_mfma_f32_16x16x32_bf16 v[112:115], v[192:195], v[212:215], v[112:115]
	v_mfma_f32_16x16x32_bf16 v[104:107], v[184:187], v[224:227], v[104:107]
	v_mfma_f32_16x16x32_bf16 v[96:99], v[192:195], v[224:227], v[96:99]
	v_mfma_f32_16x16x32_bf16 v[88:91], v[184:187], v[232:235], v[88:91]
	v_mfma_f32_16x16x32_bf16 v[80:83], v[192:195], v[232:235], v[80:83]
	v_mfma_f32_16x16x32_bf16 v[72:75], v[184:187], v[240:243], v[72:75]
	v_mfma_f32_16x16x32_bf16 v[68:71], v[192:195], v[240:243], v[68:71]
	s_setprio 0
	s_barrier
; #define PG8_STAGE(bufoff, gbase, voff) do { _Pragma("unroll") for (int _i = 0; _i < 2; ++_i) \
;         __builtin_amdgcn_global_load_lds((const unsigned*)((const char*)(gbase) + (voff)[_i]), (PG8_LAS unsigned*)(lds + (bufoff) + ldsw + _i * 8192), 16, 0, 0); } while (0)
; #define PG8_LDA(dst, b, h) do { _Pragma("unroll") for (int m = 0; m < 4; ++m) _Pragma("unroll") for (int k = 0; k < 2; ++k) dst[m][k] = *(const PG8_LAS bf16x8*)(lds + PG8_SA(b, h) + aoff + m * 2048 + k * 1024); } while (0)
; #define PG8_MMA(ai, bj, At, Bt) do { __builtin_amdgcn_s_setprio(1); _Pragma("unroll") for (int m = 0; m < 4; ++m) _Pragma("unroll") for (int n = 0; n < 2; ++n) _Pragma("unroll") for (int k = 0; k < 2; ++k) \
;         acc[ai][bj][m][n] = __builtin_amdgcn_mfma_f32_16x16x32_bf16(Bt[n][k], At[m][k], acc[ai][bj][m][n], 0, 0, 0); __builtin_amdgcn_s_setprio(0); } while (0)
; #define PG8_WAIT_V(n) asm volatile("s_waitcnt vmcnt(" #n ")" ::: "memory")
; #define PG8_WAIT_L(n) asm volatile("s_waitcnt lgkmcnt(" #n ")" ::: "memory")
; #define PG8_BAR __builtin_amdgcn_s_barrier()
; #define PG8_SCHED __builtin_amdgcn_sched_barrier(0)
; template <class Epi, class Sched, bool ALIGN_EPI = false, bool SP2 = false>
; __device__ __forceinline__ void gemm_phase(PG8_LAS unsigned char* lds, const Gemm g, const Sched& S, const Epi& E) {
;     ...
;             PG8_LDA(At, 1, 1); PG8_STAGE(PG8_SB(1, 0), b3, voffB); PG8_STAGE(PG8_SB(1, 1), b3 + hstep, voffB); PG8_STAGE(PG8_SA(1, 0), a3, voffA);
;             PG8_WAIT_V(8); PG8_WAIT_L(0); PG8_BAR; PG8_MMA(1, 0, At, B0); PG8_MMA(1, 1, At, B1); PG8_BAR; PG8_SCHED;
;     ...
;         if constexpr (ALIGN_EPI) { if (wr == 0) PG8_BAR; }
	s_add_i32 s54, s70, s56
	v_lshl_add_u64 v[162:163], v[162:163], 0, s[14:15]
	s_mov_b32 m0, s54
	ds_read_b128 v[208:211], v149 offset:49152
	ds_read_b128 v[212:215], v149 offset:50176
	ds_read_b128 v[216:219], v149 offset:51200
	ds_read_b128 v[224:227], v149 offset:52224
	ds_read_b128 v[228:231], v149 offset:53248
	ds_read_b128 v[232:235], v149 offset:54272
	ds_read_b128 v[236:239], v149 offset:55296
	ds_read_b128 v[240:243], v149 offset:56320
	global_load_lds_dwordx4 v[162:163], off
	s_add_i32 m0, s54, 0x2000
	s_add_u32 s52, s52, 0x40080
	v_lshl_add_u64 v[162:163], v[196:197], 0, s[14:15]
	s_addc_u32 s53, s53, 0
	s_add_i32 s54, s71, s56
	global_load_lds_dwordx4 v[162:163], off
	v_lshl_add_u64 v[162:163], s[52:53], 0, v[2:3]
	s_mov_b32 m0, s54
	s_nop 0
	global_load_lds_dwordx4 v[162:163], off
	v_lshl_add_u64 v[162:163], s[52:53], 0, v[132:133]
	s_add_i32 m0, s54, 0x2000
	s_nop 0
	global_load_lds_dwordx4 v[162:163], off
	v_lshl_add_u64 v[162:163], v[244:245], 0, s[14:15]
	s_mov_b32 m0, s81
	s_nop 0
	global_load_lds_dwordx4 v[162:163], off
	v_lshl_add_u64 v[162:163], v[246:247], 0, s[14:15]
	s_mov_b32 m0, s82
	s_nop 0
	global_load_lds_dwordx4 v[162:163], off
	s_waitcnt vmcnt(8)
	s_waitcnt lgkmcnt(0)
	s_barrier
	s_setprio 1
	s_waitcnt lgkmcnt(0)
	v_mfma_f32_16x16x32_bf16 v[64:67], v[142:145], v[208:211], v[64:67]
	v_mfma_f32_16x16x32_bf16 v[60:63], v[154:157], v[208:211], v[60:63]
	v_mfma_f32_16x16x32_bf16 v[52:55], v[142:145], v[216:219], v[52:55]
	v_mfma_f32_16x16x32_bf16 v[44:47], v[154:157], v[216:219], v[44:47]
	v_mfma_f32_16x16x32_bf16 v[36:39], v[142:145], v[228:231], v[36:39]
	v_mfma_f32_16x16x32_bf16 v[28:31], v[154:157], v[228:231], v[28:31]
	v_mfma_f32_16x16x32_bf16 v[20:23], v[142:145], v[236:239], v[20:23]
	v_mfma_f32_16x16x32_bf16 v[12:15], v[154:157], v[236:239], v[12:15]
	v_mfma_f32_16x16x32_bf16 v[64:67], v[150:153], v[212:215], v[64:67]
	v_mfma_f32_16x16x32_bf16 v[60:63], v[158:161], v[212:215], v[60:63]
	v_mfma_f32_16x16x32_bf16 v[52:55], v[150:153], v[224:227], v[52:55]
	v_mfma_f32_16x16x32_bf16 v[44:47], v[158:161], v[224:227], v[44:47]
	v_mfma_f32_16x16x32_bf16 v[36:39], v[150:153], v[232:235], v[36:39]
	v_mfma_f32_16x16x32_bf16 v[28:31], v[158:161], v[232:235], v[28:31]
	v_mfma_f32_16x16x32_bf16 v[20:23], v[150:153], v[240:243], v[20:23]
	v_mfma_f32_16x16x32_bf16 v[12:15], v[158:161], v[240:243], v[12:15]
	v_mfma_f32_16x16x32_bf16 v[56:59], v[180:183], v[208:211], v[56:59]
	v_mfma_f32_16x16x32_bf16 v[48:51], v[188:191], v[208:211], v[48:51]
	v_mfma_f32_16x16x32_bf16 v[40:43], v[180:183], v[216:219], v[40:43]
	v_mfma_f32_16x16x32_bf16 v[32:35], v[188:191], v[216:219], v[32:35]
	v_mfma_f32_16x16x32_bf16 v[24:27], v[180:183], v[228:231], v[24:27]
	v_mfma_f32_16x16x32_bf16 v[16:19], v[188:191], v[228:231], v[16:19]
	v_mfma_f32_16x16x32_bf16 v[8:11], v[180:183], v[236:239], v[8:11]
	v_mfma_f32_16x16x32_bf16 v[4:7], v[188:191], v[236:239], v[4:7]
	v_mfma_f32_16x16x32_bf16 v[56:59], v[184:187], v[212:215], v[56:59]
	v_mfma_f32_16x16x32_bf16 v[48:51], v[192:195], v[212:215], v[48:51]
	v_mfma_f32_16x16x32_bf16 v[40:43], v[184:187], v[224:227], v[40:43]
	v_mfma_f32_16x16x32_bf16 v[32:35], v[192:195], v[224:227], v[32:35]
	v_mfma_f32_16x16x32_bf16 v[24:27], v[184:187], v[232:235], v[24:27]
	v_mfma_f32_16x16x32_bf16 v[16:19], v[192:195], v[232:235], v[16:19]
	v_mfma_f32_16x16x32_bf16 v[8:11], v[184:187], v[240:243], v[8:11]
	v_mfma_f32_16x16x32_bf16 v[4:7], v[192:195], v[240:243], v[4:7]
	s_setprio 0
	s_add_i32 s91, s91, 2
	s_add_u32 s42, s42, 0x100
	s_addc_u32 s43, s43, 0
	s_add_u32 s89, s89, 0x100
	s_addc_u32 s90, s90, 0
	s_cmp_gt_u32 s91, 13
	s_barrier
	s_cbranch_scc0 .LBB0_188
	s_and_b64 vcc, exec, s[36:37]
	s_cbranch_vccz .LBB0_191
	s_barrier

; #define PG8_STAGE(bufoff, gbase, voff) do { _Pragma("unroll") for (int _i = 0; _i < 2; ++_i) \
;         __builtin_amdgcn_global_load_lds((const unsigned*)((const char*)(gbase) + (voff)[_i]), (PG8_LAS unsigned*)(lds + (bufoff) + ldsw + _i * 8192), 16, 0, 0); } while (0)
; #define PG8_LDA(dst, b, h) do { _Pragma("unroll") for (int m = 0; m < 4; ++m) _Pragma("unroll") for (int k = 0; k < 2; ++k) dst[m][k] = *(const PG8_LAS bf16x8*)(lds + PG8_SA(b, h) + aoff + m * 2048 + k * 1024); } while (0)
; #define PG8_LDB(dst, b, h) do { _Pragma("unroll") for (int n = 0; n < 2; ++n) _Pragma("unroll") for (int k = 0; k < 2; ++k) dst[n][k] = *(const PG8_LAS bf16x8*)(lds + PG8_SB(b, h) + boff + n * 2048 + k * 1024); } while (0)
; #define PG8_MMA(ai, bj, At, Bt) do { __builtin_amdgcn_s_setprio(1); _Pragma("unroll") for (int m = 0; m < 4; ++m) _Pragma("unroll") for (int n = 0; n < 2; ++n) _Pragma("unroll") for (int k = 0; k < 2; ++k) \
;         acc[ai][bj][m][n] = __builtin_amdgcn_mfma_f32_16x16x32_bf16(Bt[n][k], At[m][k], acc[ai][bj][m][n], 0, 0, 0); __builtin_amdgcn_s_setprio(0); } while (0)
; #define PG8_WAIT_V(n) asm volatile("s_waitcnt vmcnt(" #n ")" ::: "memory")
; #define PG8_WAIT_L(n) asm volatile("s_waitcnt lgkmcnt(" #n ")" ::: "memory")
; template <class Epi, class Sched, bool ALIGN_EPI = false, bool SP2 = false>
; __device__ __forceinline__ void gemm_phase(PG8_LAS unsigned char* lds, const Gemm g, const Sched& S, const Epi& E) {
;     ...
;             const bool last = (t == nt - 2);
;             const char* a1 = cA + (size_t)(t + 1) * kstep;
;             const char* a2 = last ? nA : cA + (size_t)(t + 2) * kstep; const char* b2 = last ? nB : cB + (size_t)(t + 2) * kstep;
;             const char* a3 = a2 + kstep; const char* b3 = b2 + kstep;
;             if (last && has_next) S.a_ready(nxt);
;             if constexpr (SP2) {
;             PG8_LDB(B0, 0, 0); PG8_LDB(B1, 0, 1); PG8_SCHED; PG8_LDA(At, 0, 0); PG8_STAGE(PG8_SA(1, 1), a1 + hstep, voffA);
;             PG8_WAIT_V(8); PG8_WAIT_L(0); PG8_BAR; PG8_MMA(0, 0, At, B0); PG8_MMA(0, 1, At, B1); PG8_BAR; PG8_SCHED;
;             PG8_LDA(At, 0, 1); PG8_STAGE(PG8_SB(0, 0), b2, voffB); PG8_STAGE(PG8_SB(0, 1), b2 + hstep, voffB); PG8_STAGE(PG8_SA(0, 0), a2, voffA);
;             PG8_WAIT_V(8); PG8_WAIT_L(0); PG8_BAR; PG8_MMA(1, 0, At, B0); PG8_MMA(1, 1, At, B1); PG8_BAR; PG8_SCHED;
.LBB0_512:
	s_add_u32 s52, s50, 0xfffc0080
	s_addc_u32 s53, s51, -1
	s_add_i32 s70, 0, 0x10000
	s_cmp_eq_u32 s89, 12
	s_cselect_b32 s55, s6, s53
	s_cselect_b32 s54, s7, s52
	s_cselect_b32 s53, s41, s85
	s_cselect_b32 s52, s45, s84
	s_add_i32 s71, 0, 0x14000
	v_add_u32_e32 v158, s70, v143
	v_add_u32_e32 v162, s71, v143
	ds_read_b128 v[146:149], v158
	ds_read_b128 v[150:153], v158 offset:1024
	ds_read_b128 v[154:157], v158 offset:2048
	ds_read_b128 v[158:161], v158 offset:3072
	ds_read_b128 v[180:183], v162
	ds_read_b128 v[184:187], v162 offset:1024
	ds_read_b128 v[188:191], v162 offset:2048
	ds_read_b128 v[192:195], v162 offset:3072
	v_lshl_add_u64 v[162:163], s[50:51], 0, v[138:139]
	s_add_i32 m0, s57, 0xc000
	ds_read_b128 v[208:211], v145
	ds_read_b128 v[212:215], v145 offset:1024
	ds_read_b128 v[216:219], v145 offset:2048
	ds_read_b128 v[224:227], v145 offset:3072
	ds_read_b128 v[228:231], v145 offset:4096
	ds_read_b128 v[232:235], v145 offset:5120
	ds_read_b128 v[236:239], v145 offset:6144
	ds_read_b128 v[240:243], v145 offset:7168
	global_load_lds_dwordx4 v[162:163], off
	v_lshl_add_u64 v[162:163], s[50:51], 0, v[140:141]
	s_add_i32 m0, s57, 0xe000
	s_nop 0
	global_load_lds_dwordx4 v[162:163], off
	s_waitcnt vmcnt(8)
	s_waitcnt lgkmcnt(0)
	s_barrier
	s_setprio 1
	s_waitcnt lgkmcnt(0)
	v_mfma_f32_16x16x32_bf16 v[128:131], v[146:149], v[208:211], v[128:131]
	v_mfma_f32_16x16x32_bf16 v[124:127], v[154:157], v[208:211], v[124:127]
	v_mfma_f32_16x16x32_bf16 v[120:123], v[146:149], v[216:219], v[120:123]
	v_mfma_f32_16x16x32_bf16 v[116:119], v[154:157], v[216:219], v[116:119]
	v_mfma_f32_16x16x32_bf16 v[104:107], v[146:149], v[228:231], v[104:107]
	v_mfma_f32_16x16x32_bf16 v[100:103], v[154:157], v[228:231], v[100:103]
	v_mfma_f32_16x16x32_bf16 v[88:91], v[146:149], v[236:239], v[88:91]
	v_mfma_f32_16x16x32_bf16 v[84:87], v[154:157], v[236:239], v[84:87]
	v_mfma_f32_16x16x32_bf16 v[128:131], v[150:153], v[212:215], v[128:131]
	v_mfma_f32_16x16x32_bf16 v[124:127], v[158:161], v[212:215], v[124:127]
	v_mfma_f32_16x16x32_bf16 v[120:123], v[150:153], v[224:227], v[120:123]
	v_mfma_f32_16x16x32_bf16 v[116:119], v[158:161], v[224:227], v[116:119]
	v_mfma_f32_16x16x32_bf16 v[104:107], v[150:153], v[232:235], v[104:107]
	v_mfma_f32_16x16x32_bf16 v[100:103], v[158:161], v[232:235], v[100:103]
	v_mfma_f32_16x16x32_bf16 v[88:91], v[150:153], v[240:243], v[88:91]
	v_mfma_f32_16x16x32_bf16 v[84:87], v[158:161], v[240:243], v[84:87]
	v_mfma_f32_16x16x32_bf16 v[112:115], v[180:183], v[208:211], v[112:115]
	v_mfma_f32_16x16x32_bf16 v[108:111], v[188:191], v[208:211], v[108:111]
	v_mfma_f32_16x16x32_bf16 v[96:99], v[180:183], v[216:219], v[96:99]
	v_mfma_f32_16x16x32_bf16 v[92:95], v[188:191], v[216:219], v[92:95]
	v_mfma_f32_16x16x32_bf16 v[80:83], v[180:183], v[228:231], v[80:83]
	v_mfma_f32_16x16x32_bf16 v[76:79], v[188:191], v[228:231], v[76:79]
	v_mfma_f32_16x16x32_bf16 v[72:75], v[180:183], v[236:239], v[72:75]
	v_mfma_f32_16x16x32_bf16 v[68:71], v[188:191], v[236:239], v[68:71]
	v_mfma_f32_16x16x32_bf16 v[112:115], v[184:187], v[212:215], v[112:115]
	v_mfma_f32_16x16x32_bf16 v[108:111], v[192:195], v[212:215], v[108:111]
	v_mfma_f32_16x16x32_bf16 v[96:99], v[184:187], v[224:227], v[96:99]
	v_mfma_f32_16x16x32_bf16 v[92:95], v[192:195], v[224:227], v[92:95]
	v_mfma_f32_16x16x32_bf16 v[80:83], v[184:187], v[232:235], v[80:83]
	v_mfma_f32_16x16x32_bf16 v[76:79], v[192:195], v[232:235], v[76:79]
	v_mfma_f32_16x16x32_bf16 v[72:75], v[184:187], v[240:243], v[72:75]
	v_mfma_f32_16x16x32_bf16 v[68:71], v[192:195], v[240:243], v[68:71]
	s_setprio 0
	s_barrier
	s_add_i32 s70, s70, s56
	v_lshl_add_u64 v[162:163], s[52:53], 0, v[2:3]
	s_mov_b32 m0, s70
	ds_read_b128 v[208:211], v145 offset:16384
	ds_read_b128 v[212:215], v145 offset:17408
	ds_read_b128 v[216:219], v145 offset:18432
	ds_read_b128 v[224:227], v145 offset:19456
	ds_read_b128 v[228:231], v145 offset:20480
	ds_read_b128 v[232:235], v145 offset:21504
	ds_read_b128 v[236:239], v145 offset:22528
	ds_read_b128 v[240:243], v145 offset:23552
	global_load_lds_dwordx4 v[162:163], off
	s_add_i32 m0, s70, 0x2000
	s_add_u32 s90, s52, 0x40000
	v_lshl_add_u64 v[196:197], s[52:53], 0, v[132:133]
	s_addc_u32 s91, s53, 0
	s_add_i32 s70, s71, s56
	global_load_lds_dwordx4 v[196:197], off
	v_lshl_add_u64 v[244:245], s[90:91], 0, v[2:3]
	s_mov_b32 m0, s70
	v_lshl_add_u64 v[246:247], s[54:55], 0, v[134:135]
	global_load_lds_dwordx4 v[244:245], off
	v_lshl_add_u64 v[244:245], s[90:91], 0, v[132:133]
	s_add_i32 m0, s70, 0x2000
	s_nop 0
	global_load_lds_dwordx4 v[244:245], off
	v_lshl_add_u64 v[244:245], s[54:55], 0, v[136:137]
	s_mov_b32 m0, s57
	s_nop 0
	global_load_lds_dwordx4 v[244:245], off
	s_mov_b32 m0, s60
	s_nop 0
	global_load_lds_dwordx4 v[246:247], off
	s_waitcnt vmcnt(8)
	s_waitcnt lgkmcnt(0)
	s_barrier
; #define PG8_STAGE(bufoff, gbase, voff) do { _Pragma("unroll") for (int _i = 0; _i < 2; ++_i) \
;         __builtin_amdgcn_global_load_lds((const unsigned*)((const char*)(gbase) + (voff)[_i]), (PG8_LAS unsigned*)(lds + (bufoff) + ldsw + _i * 8192), 16, 0, 0); } while (0)
; #define PG8_LDA(dst, b, h) do { _Pragma("unroll") for (int m = 0; m < 4; ++m) _Pragma("unroll") for (int k = 0; k < 2; ++k) dst[m][k] = *(const PG8_LAS bf16x8*)(lds + PG8_SA(b, h) + aoff + m * 2048 + k * 1024); } while (0)
; #define PG8_LDB(dst, b, h) do { _Pragma("unroll") for (int n = 0; n < 2; ++n) _Pragma("unroll") for (int k = 0; k < 2; ++k) dst[n][k] = *(const PG8_LAS bf16x8*)(lds + PG8_SB(b, h) + boff + n * 2048 + k * 1024); } while (0)
; #define PG8_MMA(ai, bj, At, Bt) do { __builtin_amdgcn_s_setprio(1); _Pragma("unroll") for (int m = 0; m < 4; ++m) _Pragma("unroll") for (int n = 0; n < 2; ++n) _Pragma("unroll") for (int k = 0; k < 2; ++k) \
;         acc[ai][bj][m][n] = __builtin_amdgcn_mfma_f32_16x16x32_bf16(Bt[n][k], At[m][k], acc[ai][bj][m][n], 0, 0, 0); __builtin_amdgcn_s_setprio(0); } while (0)
; #define PG8_WAIT_V(n) asm volatile("s_waitcnt vmcnt(" #n ")" ::: "memory")
; #define PG8_WAIT_L(n) asm volatile("s_waitcnt lgkmcnt(" #n ")" ::: "memory")
; #define PG8_BAR __builtin_amdgcn_s_barrier()
; #define PG8_SCHED __builtin_amdgcn_sched_barrier(0)
; template <class Epi, class Sched, bool ALIGN_EPI = false, bool SP2 = false>
; __device__ __forceinline__ void gemm_phase(PG8_LAS unsigned char* lds, const Gemm g, const Sched& S, const Epi& E) {
;     ...
;             PG8_WAIT_V(8); PG8_WAIT_L(0); PG8_BAR; PG8_MMA(1, 0, At, B0); PG8_MMA(1, 1, At, B1); PG8_BAR; PG8_SCHED;
;             PG8_LDB(B0, 1, 0); PG8_LDB(B1, 1, 1); PG8_SCHED; PG8_LDA(At, 1, 0); PG8_STAGE(PG8_SA(0, 1), a2 + hstep, voffA);
;             PG8_WAIT_V(8); PG8_WAIT_L(0); PG8_BAR; PG8_MMA(0, 0, At, B0); PG8_MMA(0, 1, At, B1); PG8_BAR; PG8_SCHED;
	s_setprio 1
	s_waitcnt lgkmcnt(0)
	v_mfma_f32_16x16x32_bf16 v[64:67], v[146:149], v[208:211], v[64:67]
	v_mfma_f32_16x16x32_bf16 v[60:63], v[154:157], v[208:211], v[60:63]
	v_mfma_f32_16x16x32_bf16 v[56:59], v[146:149], v[216:219], v[56:59]
	v_mfma_f32_16x16x32_bf16 v[52:55], v[154:157], v[216:219], v[52:55]
	v_mfma_f32_16x16x32_bf16 v[40:43], v[146:149], v[228:231], v[40:43]
	v_mfma_f32_16x16x32_bf16 v[36:39], v[154:157], v[228:231], v[36:39]
	v_mfma_f32_16x16x32_bf16 v[24:27], v[146:149], v[236:239], v[24:27]
	v_mfma_f32_16x16x32_bf16 v[20:23], v[154:157], v[236:239], v[20:23]
	v_mfma_f32_16x16x32_bf16 v[64:67], v[150:153], v[212:215], v[64:67]
	v_mfma_f32_16x16x32_bf16 v[60:63], v[158:161], v[212:215], v[60:63]
	v_mfma_f32_16x16x32_bf16 v[56:59], v[150:153], v[224:227], v[56:59]
	v_mfma_f32_16x16x32_bf16 v[52:55], v[158:161], v[224:227], v[52:55]
	v_mfma_f32_16x16x32_bf16 v[40:43], v[150:153], v[232:235], v[40:43]
	v_mfma_f32_16x16x32_bf16 v[36:39], v[158:161], v[232:235], v[36:39]
	v_mfma_f32_16x16x32_bf16 v[24:27], v[150:153], v[240:243], v[24:27]
	v_mfma_f32_16x16x32_bf16 v[20:23], v[158:161], v[240:243], v[20:23]
	v_mfma_f32_16x16x32_bf16 v[48:51], v[180:183], v[208:211], v[48:51]
	v_mfma_f32_16x16x32_bf16 v[44:47], v[188:191], v[208:211], v[44:47]
	v_mfma_f32_16x16x32_bf16 v[32:35], v[180:183], v[216:219], v[32:35]
	v_mfma_f32_16x16x32_bf16 v[28:31], v[188:191], v[216:219], v[28:31]
	v_mfma_f32_16x16x32_bf16 v[16:19], v[180:183], v[228:231], v[16:19]
	v_mfma_f32_16x16x32_bf16 v[12:15], v[188:191], v[228:231], v[12:15]
	v_mfma_f32_16x16x32_bf16 v[8:11], v[180:183], v[236:239], v[8:11]
	v_mfma_f32_16x16x32_bf16 v[4:7], v[188:191], v[236:239], v[4:7]
	v_mfma_f32_16x16x32_bf16 v[48:51], v[184:187], v[212:215], v[48:51]
	v_mfma_f32_16x16x32_bf16 v[44:47], v[192:195], v[212:215], v[44:47]
	v_mfma_f32_16x16x32_bf16 v[32:35], v[184:187], v[224:227], v[32:35]
	v_mfma_f32_16x16x32_bf16 v[28:31], v[192:195], v[224:227], v[28:31]
	v_mfma_f32_16x16x32_bf16 v[16:19], v[184:187], v[232:235], v[16:19]
	v_mfma_f32_16x16x32_bf16 v[12:15], v[192:195], v[232:235], v[12:15]
	v_mfma_f32_16x16x32_bf16 v[8:11], v[184:187], v[240:243], v[8:11]
	v_mfma_f32_16x16x32_bf16 v[4:7], v[192:195], v[240:243], v[4:7]
	s_setprio 0
	s_barrier
	s_add_i32 s70, 0, 0x18000
	s_add_i32 s71, 0, 0x1c000
	v_add_u32_e32 v158, s70, v143
	v_add_u32_e32 v167, s71, v143
	ds_read_b128 v[146:149], v158
	ds_read_b128 v[150:153], v158 offset:1024
	ds_read_b128 v[154:157], v158 offset:2048
	ds_read_b128 v[158:161], v158 offset:3072
	ds_read_b128 v[180:183], v167
	ds_read_b128 v[184:187], v167 offset:1024
	ds_read_b128 v[188:191], v167 offset:2048
	ds_read_b128 v[192:195], v167 offset:3072
	s_add_u32 s54, s54, 0x40000
	s_addc_u32 s55, s55, 0
	s_mov_b32 m0, s61
	v_lshl_add_u64 v[248:249], s[54:55], 0, v[136:137]
	ds_read_b128 v[208:211], v145 offset:32768
	ds_read_b128 v[212:215], v145 offset:33792
	ds_read_b128 v[216:219], v145 offset:34816
	ds_read_b128 v[224:227], v145 offset:35840
	ds_read_b128 v[228:231], v145 offset:36864
	ds_read_b128 v[232:235], v145 offset:37888
	ds_read_b128 v[236:239], v145 offset:38912
	ds_read_b128 v[240:243], v145 offset:39936
	global_load_lds_dwordx4 v[248:249], off
	v_lshl_add_u64 v[248:249], s[54:55], 0, v[134:135]
	s_mov_b32 m0, s78
	s_nop 0
	global_load_lds_dwordx4 v[248:249], off
	s_waitcnt vmcnt(8)
	s_waitcnt lgkmcnt(0)
	s_barrier
	s_setprio 1
	s_waitcnt lgkmcnt(0)
	v_mfma_f32_16x16x32_bf16 v[128:131], v[146:149], v[208:211], v[128:131]
	v_mfma_f32_16x16x32_bf16 v[124:127], v[154:157], v[208:211], v[124:127]
	v_mfma_f32_16x16x32_bf16 v[120:123], v[146:149], v[216:219], v[120:123]
	v_mfma_f32_16x16x32_bf16 v[116:119], v[154:157], v[216:219], v[116:119]
	v_mfma_f32_16x16x32_bf16 v[104:107], v[146:149], v[228:231], v[104:107]
	v_mfma_f32_16x16x32_bf16 v[100:103], v[154:157], v[228:231], v[100:103]
	v_mfma_f32_16x16x32_bf16 v[88:91], v[146:149], v[236:239], v[88:91]
	v_mfma_f32_16x16x32_bf16 v[84:87], v[154:157], v[236:239], v[84:87]
	v_mfma_f32_16x16x32_bf16 v[128:131], v[150:153], v[212:215], v[128:131]
	v_mfma_f32_16x16x32_bf16 v[124:127], v[158:161], v[212:215], v[124:127]
	v_mfma_f32_16x16x32_bf16 v[120:123], v[150:153], v[224:227], v[120:123]
	v_mfma_f32_16x16x32_bf16 v[116:119], v[158:161], v[224:227], v[116:119]
	v_mfma_f32_16x16x32_bf16 v[104:107], v[150:153], v[232:235], v[104:107]
	v_mfma_f32_16x16x32_bf16 v[100:103], v[158:161], v[232:235], v[100:103]
	v_mfma_f32_16x16x32_bf16 v[88:91], v[150:153], v[240:243], v[88:91]
	v_mfma_f32_16x16x32_bf16 v[84:87], v[158:161], v[240:243], v[84:87]
	v_mfma_f32_16x16x32_bf16 v[112:115], v[180:183], v[208:211], v[112:115]
	v_mfma_f32_16x16x32_bf16 v[108:111], v[188:191], v[208:211], v[108:111]
	v_mfma_f32_16x16x32_bf16 v[96:99], v[180:183], v[216:219], v[96:99]
	v_mfma_f32_16x16x32_bf16 v[92:95], v[188:191], v[216:219], v[92:95]
	v_mfma_f32_16x16x32_bf16 v[80:83], v[180:183], v[228:231], v[80:83]
	v_mfma_f32_16x16x32_bf16 v[76:79], v[188:191], v[228:231], v[76:79]
	v_mfma_f32_16x16x32_bf16 v[72:75], v[180:183], v[236:239], v[72:75]
	v_mfma_f32_16x16x32_bf16 v[68:71], v[188:191], v[236:239], v[68:71]
	v_mfma_f32_16x16x32_bf16 v[112:115], v[184:187], v[212:215], v[112:115]
	v_mfma_f32_16x16x32_bf16 v[108:111], v[192:195], v[212:215], v[108:111]
	v_mfma_f32_16x16x32_bf16 v[96:99], v[184:187], v[224:227], v[96:99]
	v_mfma_f32_16x16x32_bf16 v[92:95], v[192:195], v[224:227], v[92:95]
	v_mfma_f32_16x16x32_bf16 v[80:83], v[184:187], v[232:235], v[80:83]
	v_mfma_f32_16x16x32_bf16 v[76:79], v[192:195], v[232:235], v[76:79]
	v_mfma_f32_16x16x32_bf16 v[72:75], v[184:187], v[240:243], v[72:75]
	v_mfma_f32_16x16x32_bf16 v[68:71], v[192:195], v[240:243], v[68:71]
	s_setprio 0
	s_barrier
; #define PG8_STAGE(bufoff, gbase, voff) do { _Pragma("unroll") for (int _i = 0; _i < 2; ++_i) \
;         __builtin_amdgcn_global_load_lds((const unsigned*)((const char*)(gbase) + (voff)[_i]), (PG8_LAS unsigned*)(lds + (bufoff) + ldsw + _i * 8192), 16, 0, 0); } while (0)
; #define PG8_LDA(dst, b, h) do { _Pragma("unroll") for (int m = 0; m < 4; ++m) _Pragma("unroll") for (int k = 0; k < 2; ++k) dst[m][k] = *(const PG8_LAS bf16x8*)(lds + PG8_SA(b, h) + aoff + m * 2048 + k * 1024); } while (0)
; #define PG8_MMA(ai, bj, At, Bt) do { __builtin_amdgcn_s_setprio(1); _Pragma("unroll") for (int m = 0; m < 4; ++m) _Pragma("unroll") for (int n = 0; n < 2; ++n) _Pragma("unroll") for (int k = 0; k < 2; ++k) \
;         acc[ai][bj][m][n] = __builtin_amdgcn_mfma_f32_16x16x32_bf16(Bt[n][k], At[m][k], acc[ai][bj][m][n], 0, 0, 0); __builtin_amdgcn_s_setprio(0); } while (0)
; #define PG8_WAIT_V(n) asm volatile("s_waitcnt vmcnt(" #n ")" ::: "memory")
; #define PG8_WAIT_L(n) asm volatile("s_waitcnt lgkmcnt(" #n ")" ::: "memory")
; #define PG8_BAR __builtin_amdgcn_s_barrier()
; #define PG8_SCHED __builtin_amdgcn_sched_barrier(0)
; template <class Epi, class Sched, bool ALIGN_EPI = false, bool SP2 = false>
; __device__ __forceinline__ void gemm_phase(PG8_LAS unsigned char* lds, const Gemm g, const Sched& S, const Epi& E) {
;     ...
;             PG8_LDA(At, 1, 1); PG8_STAGE(PG8_SB(1, 0), b3, voffB); PG8_STAGE(PG8_SB(1, 1), b3 + hstep, voffB); PG8_STAGE(PG8_SA(1, 0), a3, voffA);
;             PG8_WAIT_V(8); PG8_WAIT_L(0); PG8_BAR; PG8_MMA(1, 0, At, B0); PG8_MMA(1, 1, At, B1); PG8_BAR; PG8_SCHED;
;     ...
;         if constexpr (ALIGN_EPI) { if (wr == 0) PG8_BAR; }
	s_add_i32 s54, s70, s56
	v_lshl_add_u64 v[162:163], v[162:163], 0, s[14:15]
	s_mov_b32 m0, s54
	ds_read_b128 v[208:211], v145 offset:49152
	ds_read_b128 v[212:215], v145 offset:50176
	ds_read_b128 v[216:219], v145 offset:51200
	ds_read_b128 v[224:227], v145 offset:52224
	ds_read_b128 v[228:231], v145 offset:53248
	ds_read_b128 v[232:235], v145 offset:54272
	ds_read_b128 v[236:239], v145 offset:55296
	ds_read_b128 v[240:243], v145 offset:56320
	global_load_lds_dwordx4 v[162:163], off
	s_add_i32 m0, s54, 0x2000
	s_add_u32 s52, s52, 0x40080
	v_lshl_add_u64 v[162:163], v[196:197], 0, s[14:15]
	s_addc_u32 s53, s53, 0
	s_add_i32 s54, s71, s56
	global_load_lds_dwordx4 v[162:163], off
	v_lshl_add_u64 v[162:163], s[52:53], 0, v[2:3]
	s_mov_b32 m0, s54
	s_nop 0
	global_load_lds_dwordx4 v[162:163], off
	v_lshl_add_u64 v[162:163], s[52:53], 0, v[132:133]
	s_add_i32 m0, s54, 0x2000
	s_nop 0
	global_load_lds_dwordx4 v[162:163], off
	v_lshl_add_u64 v[162:163], v[244:245], 0, s[14:15]
	s_mov_b32 m0, s79
	s_nop 0
	global_load_lds_dwordx4 v[162:163], off
	v_lshl_add_u64 v[162:163], v[246:247], 0, s[14:15]
	s_mov_b32 m0, s80
	s_nop 0
	global_load_lds_dwordx4 v[162:163], off
	s_waitcnt vmcnt(8)
	s_waitcnt lgkmcnt(0)
	s_barrier
	s_setprio 1
	s_waitcnt lgkmcnt(0)
	v_mfma_f32_16x16x32_bf16 v[64:67], v[146:149], v[208:211], v[64:67]
	v_mfma_f32_16x16x32_bf16 v[60:63], v[154:157], v[208:211], v[60:63]
	v_mfma_f32_16x16x32_bf16 v[56:59], v[146:149], v[216:219], v[56:59]
	v_mfma_f32_16x16x32_bf16 v[52:55], v[154:157], v[216:219], v[52:55]
	v_mfma_f32_16x16x32_bf16 v[40:43], v[146:149], v[228:231], v[40:43]
	v_mfma_f32_16x16x32_bf16 v[36:39], v[154:157], v[228:231], v[36:39]
	v_mfma_f32_16x16x32_bf16 v[24:27], v[146:149], v[236:239], v[24:27]
	v_mfma_f32_16x16x32_bf16 v[20:23], v[154:157], v[236:239], v[20:23]
	v_mfma_f32_16x16x32_bf16 v[64:67], v[150:153], v[212:215], v[64:67]
	v_mfma_f32_16x16x32_bf16 v[60:63], v[158:161], v[212:215], v[60:63]
	v_mfma_f32_16x16x32_bf16 v[56:59], v[150:153], v[224:227], v[56:59]
	v_mfma_f32_16x16x32_bf16 v[52:55], v[158:161], v[224:227], v[52:55]
	v_mfma_f32_16x16x32_bf16 v[40:43], v[150:153], v[232:235], v[40:43]
	v_mfma_f32_16x16x32_bf16 v[36:39], v[158:161], v[232:235], v[36:39]
	v_mfma_f32_16x16x32_bf16 v[24:27], v[150:153], v[240:243], v[24:27]
	v_mfma_f32_16x16x32_bf16 v[20:23], v[158:161], v[240:243], v[20:23]
	v_mfma_f32_16x16x32_bf16 v[48:51], v[180:183], v[208:211], v[48:51]
	v_mfma_f32_16x16x32_bf16 v[44:47], v[188:191], v[208:211], v[44:47]
	v_mfma_f32_16x16x32_bf16 v[32:35], v[180:183], v[216:219], v[32:35]
	v_mfma_f32_16x16x32_bf16 v[28:31], v[188:191], v[216:219], v[28:31]
	v_mfma_f32_16x16x32_bf16 v[16:19], v[180:183], v[228:231], v[16:19]
	v_mfma_f32_16x16x32_bf16 v[12:15], v[188:191], v[228:231], v[12:15]
	v_mfma_f32_16x16x32_bf16 v[8:11], v[180:183], v[236:239], v[8:11]
	v_mfma_f32_16x16x32_bf16 v[4:7], v[188:191], v[236:239], v[4:7]
	v_mfma_f32_16x16x32_bf16 v[48:51], v[184:187], v[212:215], v[48:51]
	v_mfma_f32_16x16x32_bf16 v[44:47], v[192:195], v[212:215], v[44:47]
	v_mfma_f32_16x16x32_bf16 v[32:35], v[184:187], v[224:227], v[32:35]
	v_mfma_f32_16x16x32_bf16 v[28:31], v[192:195], v[224:227], v[28:31]
	v_mfma_f32_16x16x32_bf16 v[16:19], v[184:187], v[232:235], v[16:19]
	v_mfma_f32_16x16x32_bf16 v[12:15], v[192:195], v[232:235], v[12:15]
	v_mfma_f32_16x16x32_bf16 v[8:11], v[184:187], v[240:243], v[8:11]
	v_mfma_f32_16x16x32_bf16 v[4:7], v[192:195], v[240:243], v[4:7]
	s_setprio 0
	s_add_i32 s89, s89, 2
	s_add_u32 s50, s50, 0x100
	s_addc_u32 s51, s51, 0
	s_add_u32 s84, s84, 0x100
	s_addc_u32 s85, s85, 0
	s_cmp_gt_u32 s89, 13
	s_barrier
	s_cbranch_scc0 .LBB0_512
	s_and_b64 vcc, exec, s[36:37]
	s_cbranch_vccz .LBB0_515
	s_barrier

; #define PG8_STAGE(bufoff, gbase, voff) do { _Pragma("unroll") for (int _i = 0; _i < 2; ++_i) \
;         __builtin_amdgcn_global_load_lds((const unsigned*)((const char*)(gbase) + (voff)[_i]), (PG8_LAS unsigned*)(lds + (bufoff) + ldsw + _i * 8192), 16, 0, 0); } while (0)
; #define PG8_LDA(dst, b, h) do { _Pragma("unroll") for (int m = 0; m < 4; ++m) _Pragma("unroll") for (int k = 0; k < 2; ++k) dst[m][k] = *(const PG8_LAS bf16x8*)(lds + PG8_SA(b, h) + aoff + m * 2048 + k * 1024); } while (0)
; #define PG8_LDB(dst, b, h) do { _Pragma("unroll") for (int n = 0; n < 2; ++n) _Pragma("unroll") for (int k = 0; k < 2; ++k) dst[n][k] = *(const PG8_LAS bf16x8*)(lds + PG8_SB(b, h) + boff + n * 2048 + k * 1024); } while (0)
; #define PG8_MMA(ai, bj, At, Bt) do { __builtin_amdgcn_s_setprio(1); _Pragma("unroll") for (int m = 0; m < 4; ++m) _Pragma("unroll") for (int n = 0; n < 2; ++n) _Pragma("unroll") for (int k = 0; k < 2; ++k) \
;         acc[ai][bj][m][n] = __builtin_amdgcn_mfma_f32_16x16x32_bf16(Bt[n][k], At[m][k], acc[ai][bj][m][n], 0, 0, 0); __builtin_amdgcn_s_setprio(0); } while (0)
; #define PG8_WAIT_V(n) asm volatile("s_waitcnt vmcnt(" #n ")" ::: "memory")
; #define PG8_WAIT_L(n) asm volatile("s_waitcnt lgkmcnt(" #n ")" ::: "memory")
; template <class Epi, class Sched, bool ALIGN_EPI = false, bool SP2 = false>
; __device__ __forceinline__ void gemm_phase(PG8_LAS unsigned char* lds, const Gemm g, const Sched& S, const Epi& E) {
;     ...
;             const bool last = (t == nt - 2);
;             const char* a1 = cA + (size_t)(t + 1) * kstep;
;             const char* a2 = last ? nA : cA + (size_t)(t + 2) * kstep; const char* b2 = last ? nB : cB + (size_t)(t + 2) * kstep;
;             const char* a3 = a2 + kstep; const char* b3 = b2 + kstep;
;             if (last && has_next) S.a_ready(nxt);
;             if constexpr (SP2) {
;             PG8_LDB(B0, 0, 0); PG8_LDB(B1, 0, 1); PG8_SCHED; PG8_LDA(At, 0, 0); PG8_STAGE(PG8_SA(1, 1), a1 + hstep, voffA);
;             PG8_WAIT_V(8); PG8_WAIT_L(0); PG8_BAR; PG8_MMA(0, 0, At, B0); PG8_MMA(0, 1, At, B1); PG8_BAR; PG8_SCHED;
;             PG8_LDA(At, 0, 1); PG8_STAGE(PG8_SB(0, 0), b2, voffB); PG8_STAGE(PG8_SB(0, 1), b2 + hstep, voffB); PG8_STAGE(PG8_SA(0, 0), a2, voffA);
;             PG8_WAIT_V(8); PG8_WAIT_L(0); PG8_BAR; PG8_MMA(1, 0, At, B0); PG8_MMA(1, 1, At, B1); PG8_BAR; PG8_SCHED;
.LBB0_698:
	s_add_u32 s52, s50, 0xfffc0080
	s_addc_u32 s53, s51, -1
	s_add_i32 s70, 0, 0x10000
	s_cmp_eq_u32 s89, 12
	s_cselect_b32 s55, s6, s53
	s_cselect_b32 s54, s7, s52
	v_add_u32_e32 v2, s70, v168
	s_cselect_b32 s53, s43, s85
	s_cselect_b32 s52, s45, s84
	s_add_i32 s71, 0, 0x14000
	ds_read_b128 v[100:103], v2
	ds_read_b128 v[112:115], v2 offset:1024
	ds_read_b128 v[124:127], v2 offset:2048
	ds_read_b128 v[136:139], v2 offset:3072
	v_add_u32_e32 v2, s71, v168
	ds_read_b128 v[148:151], v2
	ds_read_b128 v[152:155], v2 offset:1024
	ds_read_b128 v[156:159], v2 offset:2048
	ds_read_b128 v[188:191], v2 offset:3072
	v_lshl_add_u64 v[240:241], s[50:51], 0, v[184:185]
	s_add_i32 m0, s57, 0xc000
	ds_read_b128 v[192:195], v197
	ds_read_b128 v[208:211], v197 offset:1024
	ds_read_b128 v[212:215], v197 offset:2048
	ds_read_b128 v[216:219], v197 offset:3072
	ds_read_b128 v[224:227], v197 offset:4096
	ds_read_b128 v[228:231], v197 offset:5120
	ds_read_b128 v[232:235], v197 offset:6144
	ds_read_b128 v[236:239], v197 offset:7168
	global_load_lds_dwordx4 v[240:241], off
	v_lshl_add_u64 v[240:241], s[50:51], 0, v[186:187]
	s_add_i32 m0, s57, 0xe000
	s_nop 0
	global_load_lds_dwordx4 v[240:241], off
	s_waitcnt vmcnt(8)
	s_waitcnt lgkmcnt(0)
	s_barrier
	s_setprio 1
	s_waitcnt lgkmcnt(0)
	v_mfma_f32_16x16x32_bf16 v[144:147], v[100:103], v[192:195], v[144:147]
	v_mfma_f32_16x16x32_bf16 v[140:143], v[124:127], v[192:195], v[140:143]
	v_mfma_f32_16x16x32_bf16 v[120:123], v[100:103], v[212:215], v[120:123]
	v_mfma_f32_16x16x32_bf16 v[116:119], v[124:127], v[212:215], v[116:119]
	v_mfma_f32_16x16x32_bf16 v[96:99], v[100:103], v[224:227], v[96:99]
	v_mfma_f32_16x16x32_bf16 v[92:95], v[124:127], v[224:227], v[92:95]
	v_mfma_f32_16x16x32_bf16 v[80:83], v[100:103], v[232:235], v[80:83]
	v_mfma_f32_16x16x32_bf16 v[76:79], v[124:127], v[232:235], v[76:79]
	v_mfma_f32_16x16x32_bf16 v[144:147], v[112:115], v[208:211], v[144:147]
	v_mfma_f32_16x16x32_bf16 v[140:143], v[136:139], v[208:211], v[140:143]
	v_mfma_f32_16x16x32_bf16 v[120:123], v[112:115], v[216:219], v[120:123]
	v_mfma_f32_16x16x32_bf16 v[116:119], v[136:139], v[216:219], v[116:119]
	v_mfma_f32_16x16x32_bf16 v[96:99], v[112:115], v[228:231], v[96:99]
	v_mfma_f32_16x16x32_bf16 v[92:95], v[136:139], v[228:231], v[92:95]
	v_mfma_f32_16x16x32_bf16 v[80:83], v[112:115], v[236:239], v[80:83]
	v_mfma_f32_16x16x32_bf16 v[76:79], v[136:139], v[236:239], v[76:79]
	v_mfma_f32_16x16x32_bf16 v[132:135], v[148:151], v[192:195], v[132:135]
	v_mfma_f32_16x16x32_bf16 v[128:131], v[156:159], v[192:195], v[128:131]
	v_mfma_f32_16x16x32_bf16 v[108:111], v[148:151], v[212:215], v[108:111]
	v_mfma_f32_16x16x32_bf16 v[104:107], v[156:159], v[212:215], v[104:107]
	v_mfma_f32_16x16x32_bf16 v[88:91], v[148:151], v[224:227], v[88:91]
	v_mfma_f32_16x16x32_bf16 v[84:87], v[156:159], v[224:227], v[84:87]
	v_mfma_f32_16x16x32_bf16 v[72:75], v[148:151], v[232:235], v[72:75]
	v_mfma_f32_16x16x32_bf16 v[68:71], v[156:159], v[232:235], v[68:71]
	v_mfma_f32_16x16x32_bf16 v[132:135], v[152:155], v[208:211], v[132:135]
	v_mfma_f32_16x16x32_bf16 v[128:131], v[188:191], v[208:211], v[128:131]
	v_mfma_f32_16x16x32_bf16 v[108:111], v[152:155], v[216:219], v[108:111]
	v_mfma_f32_16x16x32_bf16 v[104:107], v[188:191], v[216:219], v[104:107]
	v_mfma_f32_16x16x32_bf16 v[88:91], v[152:155], v[228:231], v[88:91]
	v_mfma_f32_16x16x32_bf16 v[84:87], v[188:191], v[228:231], v[84:87]
	v_mfma_f32_16x16x32_bf16 v[72:75], v[152:155], v[236:239], v[72:75]
	v_mfma_f32_16x16x32_bf16 v[68:71], v[188:191], v[236:239], v[68:71]
	s_setprio 0
	s_barrier
	s_add_i32 s70, s70, s56
	v_lshl_add_u64 v[240:241], s[52:53], 0, v[180:181]
	s_mov_b32 m0, s70
	ds_read_b128 v[192:195], v197 offset:16384
	ds_read_b128 v[208:211], v197 offset:17408
	ds_read_b128 v[212:215], v197 offset:18432
	ds_read_b128 v[216:219], v197 offset:19456
	ds_read_b128 v[224:227], v197 offset:20480
	ds_read_b128 v[228:231], v197 offset:21504
	ds_read_b128 v[232:235], v197 offset:22528
	ds_read_b128 v[236:239], v197 offset:23552
	global_load_lds_dwordx4 v[240:241], off
	s_add_i32 m0, s70, 0x2000
	s_add_u32 s90, s52, 0x40000
	v_lshl_add_u64 v[242:243], s[52:53], 0, v[160:161]
	s_addc_u32 s91, s53, 0
	s_add_i32 s70, s71, s56
	global_load_lds_dwordx4 v[242:243], off
	v_lshl_add_u64 v[244:245], s[90:91], 0, v[180:181]
	s_mov_b32 m0, s70
	v_lshl_add_u64 v[246:247], s[54:55], 0, v[162:163]
	global_load_lds_dwordx4 v[244:245], off
	v_lshl_add_u64 v[244:245], s[90:91], 0, v[160:161]
	s_add_i32 m0, s70, 0x2000
	s_nop 0
	global_load_lds_dwordx4 v[244:245], off
	v_lshl_add_u64 v[244:245], s[54:55], 0, v[182:183]
	s_mov_b32 m0, s57
	s_nop 0
	global_load_lds_dwordx4 v[244:245], off
	s_mov_b32 m0, s60
	s_nop 0
	global_load_lds_dwordx4 v[246:247], off
	s_waitcnt vmcnt(8)
	s_waitcnt lgkmcnt(0)
	s_barrier
; #define PG8_STAGE(bufoff, gbase, voff) do { _Pragma("unroll") for (int _i = 0; _i < 2; ++_i) \
;         __builtin_amdgcn_global_load_lds((const unsigned*)((const char*)(gbase) + (voff)[_i]), (PG8_LAS unsigned*)(lds + (bufoff) + ldsw + _i * 8192), 16, 0, 0); } while (0)
; #define PG8_LDA(dst, b, h) do { _Pragma("unroll") for (int m = 0; m < 4; ++m) _Pragma("unroll") for (int k = 0; k < 2; ++k) dst[m][k] = *(const PG8_LAS bf16x8*)(lds + PG8_SA(b, h) + aoff + m * 2048 + k * 1024); } while (0)
; #define PG8_LDB(dst, b, h) do { _Pragma("unroll") for (int n = 0; n < 2; ++n) _Pragma("unroll") for (int k = 0; k < 2; ++k) dst[n][k] = *(const PG8_LAS bf16x8*)(lds + PG8_SB(b, h) + boff + n * 2048 + k * 1024); } while (0)
; #define PG8_MMA(ai, bj, At, Bt) do { __builtin_amdgcn_s_setprio(1); _Pragma("unroll") for (int m = 0; m < 4; ++m) _Pragma("unroll") for (int n = 0; n < 2; ++n) _Pragma("unroll") for (int k = 0; k < 2; ++k) \
;         acc[ai][bj][m][n] = __builtin_amdgcn_mfma_f32_16x16x32_bf16(Bt[n][k], At[m][k], acc[ai][bj][m][n], 0, 0, 0); __builtin_amdgcn_s_setprio(0); } while (0)
; #define PG8_WAIT_V(n) asm volatile("s_waitcnt vmcnt(" #n ")" ::: "memory")
; #define PG8_WAIT_L(n) asm volatile("s_waitcnt lgkmcnt(" #n ")" ::: "memory")
; #define PG8_BAR __builtin_amdgcn_s_barrier()
; #define PG8_SCHED __builtin_amdgcn_sched_barrier(0)
; template <class Epi, class Sched, bool ALIGN_EPI = false, bool SP2 = false>
; __device__ __forceinline__ void gemm_phase(PG8_LAS unsigned char* lds, const Gemm g, const Sched& S, const Epi& E) {
;     ...
;             PG8_WAIT_V(8); PG8_WAIT_L(0); PG8_BAR; PG8_MMA(1, 0, At, B0); PG8_MMA(1, 1, At, B1); PG8_BAR; PG8_SCHED;
;             PG8_LDB(B0, 1, 0); PG8_LDB(B1, 1, 1); PG8_SCHED; PG8_LDA(At, 1, 0); PG8_STAGE(PG8_SA(0, 1), a2 + hstep, voffA);
;             PG8_WAIT_V(8); PG8_WAIT_L(0); PG8_BAR; PG8_MMA(0, 0, At, B0); PG8_MMA(0, 1, At, B1); PG8_BAR; PG8_SCHED;
	s_setprio 1
	s_waitcnt lgkmcnt(0)
	v_mfma_f32_16x16x32_bf16 v[64:67], v[100:103], v[192:195], v[64:67]
	v_mfma_f32_16x16x32_bf16 v[60:63], v[124:127], v[192:195], v[60:63]
	v_mfma_f32_16x16x32_bf16 v[48:51], v[100:103], v[212:215], v[48:51]
	v_mfma_f32_16x16x32_bf16 v[44:47], v[124:127], v[212:215], v[44:47]
	v_mfma_f32_16x16x32_bf16 v[32:35], v[100:103], v[224:227], v[32:35]
	v_mfma_f32_16x16x32_bf16 v[28:31], v[124:127], v[224:227], v[28:31]
	v_mfma_f32_16x16x32_bf16 v[16:19], v[100:103], v[232:235], v[16:19]
	v_mfma_f32_16x16x32_bf16 v[12:15], v[124:127], v[232:235], v[12:15]
	v_mfma_f32_16x16x32_bf16 v[64:67], v[112:115], v[208:211], v[64:67]
	v_mfma_f32_16x16x32_bf16 v[60:63], v[136:139], v[208:211], v[60:63]
	v_mfma_f32_16x16x32_bf16 v[48:51], v[112:115], v[216:219], v[48:51]
	v_mfma_f32_16x16x32_bf16 v[44:47], v[136:139], v[216:219], v[44:47]
	v_mfma_f32_16x16x32_bf16 v[32:35], v[112:115], v[228:231], v[32:35]
	v_mfma_f32_16x16x32_bf16 v[28:31], v[136:139], v[228:231], v[28:31]
	v_mfma_f32_16x16x32_bf16 v[16:19], v[112:115], v[236:239], v[16:19]
	v_mfma_f32_16x16x32_bf16 v[12:15], v[136:139], v[236:239], v[12:15]
	v_mfma_f32_16x16x32_bf16 v[56:59], v[148:151], v[192:195], v[56:59]
	v_mfma_f32_16x16x32_bf16 v[52:55], v[156:159], v[192:195], v[52:55]
	v_mfma_f32_16x16x32_bf16 v[40:43], v[148:151], v[212:215], v[40:43]
	v_mfma_f32_16x16x32_bf16 v[36:39], v[156:159], v[212:215], v[36:39]
	v_mfma_f32_16x16x32_bf16 v[24:27], v[148:151], v[224:227], v[24:27]
	v_mfma_f32_16x16x32_bf16 v[20:23], v[156:159], v[224:227], v[20:23]
	v_mfma_f32_16x16x32_bf16 v[8:11], v[148:151], v[232:235], v[8:11]
	v_mfma_f32_16x16x32_bf16 v[4:7], v[156:159], v[232:235], v[4:7]
	v_mfma_f32_16x16x32_bf16 v[56:59], v[152:155], v[208:211], v[56:59]
	v_mfma_f32_16x16x32_bf16 v[52:55], v[188:191], v[208:211], v[52:55]
	v_mfma_f32_16x16x32_bf16 v[40:43], v[152:155], v[216:219], v[40:43]
	v_mfma_f32_16x16x32_bf16 v[36:39], v[188:191], v[216:219], v[36:39]
	v_mfma_f32_16x16x32_bf16 v[24:27], v[152:155], v[228:231], v[24:27]
	v_mfma_f32_16x16x32_bf16 v[20:23], v[188:191], v[228:231], v[20:23]
	v_mfma_f32_16x16x32_bf16 v[8:11], v[152:155], v[236:239], v[8:11]
	v_mfma_f32_16x16x32_bf16 v[4:7], v[188:191], v[236:239], v[4:7]
	s_setprio 0
	s_barrier
	s_add_i32 s70, 0, 0x18000
	v_add_u32_e32 v2, s70, v168
	s_add_i32 s71, 0, 0x1c000
	ds_read_b128 v[100:103], v2
	ds_read_b128 v[112:115], v2 offset:1024
	ds_read_b128 v[124:127], v2 offset:2048
	ds_read_b128 v[136:139], v2 offset:3072
	v_add_u32_e32 v2, s71, v168
	ds_read_b128 v[148:151], v2
	ds_read_b128 v[152:155], v2 offset:1024
	ds_read_b128 v[156:159], v2 offset:2048
	ds_read_b128 v[188:191], v2 offset:3072
	s_add_u32 s54, s54, 0x40000
	s_addc_u32 s55, s55, 0
	s_mov_b32 m0, s61
	v_lshl_add_u64 v[248:249], s[54:55], 0, v[182:183]
	ds_read_b128 v[192:195], v197 offset:32768
	ds_read_b128 v[208:211], v197 offset:33792
	ds_read_b128 v[212:215], v197 offset:34816
	ds_read_b128 v[216:219], v197 offset:35840
	ds_read_b128 v[224:227], v197 offset:36864
	ds_read_b128 v[228:231], v197 offset:37888
	ds_read_b128 v[232:235], v197 offset:38912
	ds_read_b128 v[236:239], v197 offset:39936
	global_load_lds_dwordx4 v[248:249], off
	v_lshl_add_u64 v[248:249], s[54:55], 0, v[162:163]
	s_mov_b32 m0, s78
	s_nop 0
	global_load_lds_dwordx4 v[248:249], off
	s_waitcnt vmcnt(8)
	s_waitcnt lgkmcnt(0)
	s_barrier
	s_setprio 1
	s_waitcnt lgkmcnt(0)
	v_mfma_f32_16x16x32_bf16 v[144:147], v[100:103], v[192:195], v[144:147]
	v_mfma_f32_16x16x32_bf16 v[140:143], v[124:127], v[192:195], v[140:143]
	v_mfma_f32_16x16x32_bf16 v[120:123], v[100:103], v[212:215], v[120:123]
	v_mfma_f32_16x16x32_bf16 v[116:119], v[124:127], v[212:215], v[116:119]
	v_mfma_f32_16x16x32_bf16 v[96:99], v[100:103], v[224:227], v[96:99]
	v_mfma_f32_16x16x32_bf16 v[92:95], v[124:127], v[224:227], v[92:95]
	v_mfma_f32_16x16x32_bf16 v[80:83], v[100:103], v[232:235], v[80:83]
	v_mfma_f32_16x16x32_bf16 v[76:79], v[124:127], v[232:235], v[76:79]
	v_mfma_f32_16x16x32_bf16 v[144:147], v[112:115], v[208:211], v[144:147]
	v_mfma_f32_16x16x32_bf16 v[140:143], v[136:139], v[208:211], v[140:143]
	v_mfma_f32_16x16x32_bf16 v[120:123], v[112:115], v[216:219], v[120:123]
	v_mfma_f32_16x16x32_bf16 v[116:119], v[136:139], v[216:219], v[116:119]
	v_mfma_f32_16x16x32_bf16 v[96:99], v[112:115], v[228:231], v[96:99]
	v_mfma_f32_16x16x32_bf16 v[92:95], v[136:139], v[228:231], v[92:95]
	v_mfma_f32_16x16x32_bf16 v[80:83], v[112:115], v[236:239], v[80:83]
	v_mfma_f32_16x16x32_bf16 v[76:79], v[136:139], v[236:239], v[76:79]
	v_mfma_f32_16x16x32_bf16 v[132:135], v[148:151], v[192:195], v[132:135]
	v_mfma_f32_16x16x32_bf16 v[128:131], v[156:159], v[192:195], v[128:131]
	v_mfma_f32_16x16x32_bf16 v[108:111], v[148:151], v[212:215], v[108:111]
	v_mfma_f32_16x16x32_bf16 v[104:107], v[156:159], v[212:215], v[104:107]
	v_mfma_f32_16x16x32_bf16 v[88:91], v[148:151], v[224:227], v[88:91]
	v_mfma_f32_16x16x32_bf16 v[84:87], v[156:159], v[224:227], v[84:87]
	v_mfma_f32_16x16x32_bf16 v[72:75], v[148:151], v[232:235], v[72:75]
	v_mfma_f32_16x16x32_bf16 v[68:71], v[156:159], v[232:235], v[68:71]
	v_mfma_f32_16x16x32_bf16 v[132:135], v[152:155], v[208:211], v[132:135]
	v_mfma_f32_16x16x32_bf16 v[128:131], v[188:191], v[208:211], v[128:131]
	v_mfma_f32_16x16x32_bf16 v[108:111], v[152:155], v[216:219], v[108:111]
	v_mfma_f32_16x16x32_bf16 v[104:107], v[188:191], v[216:219], v[104:107]
	v_mfma_f32_16x16x32_bf16 v[88:91], v[152:155], v[228:231], v[88:91]
	v_mfma_f32_16x16x32_bf16 v[84:87], v[188:191], v[228:231], v[84:87]
	v_mfma_f32_16x16x32_bf16 v[72:75], v[152:155], v[236:239], v[72:75]
	v_mfma_f32_16x16x32_bf16 v[68:71], v[188:191], v[236:239], v[68:71]
	s_setprio 0
	s_barrier
; #define PG8_STAGE(bufoff, gbase, voff) do { _Pragma("unroll") for (int _i = 0; _i < 2; ++_i) \
;         __builtin_amdgcn_global_load_lds((const unsigned*)((const char*)(gbase) + (voff)[_i]), (PG8_LAS unsigned*)(lds + (bufoff) + ldsw + _i * 8192), 16, 0, 0); } while (0)
; #define PG8_LDA(dst, b, h) do { _Pragma("unroll") for (int m = 0; m < 4; ++m) _Pragma("unroll") for (int k = 0; k < 2; ++k) dst[m][k] = *(const PG8_LAS bf16x8*)(lds + PG8_SA(b, h) + aoff + m * 2048 + k * 1024); } while (0)
; #define PG8_MMA(ai, bj, At, Bt) do { __builtin_amdgcn_s_setprio(1); _Pragma("unroll") for (int m = 0; m < 4; ++m) _Pragma("unroll") for (int n = 0; n < 2; ++n) _Pragma("unroll") for (int k = 0; k < 2; ++k) \
;         acc[ai][bj][m][n] = __builtin_amdgcn_mfma_f32_16x16x32_bf16(Bt[n][k], At[m][k], acc[ai][bj][m][n], 0, 0, 0); __builtin_amdgcn_s_setprio(0); } while (0)
; #define PG8_WAIT_V(n) asm volatile("s_waitcnt vmcnt(" #n ")" ::: "memory")
; #define PG8_WAIT_L(n) asm volatile("s_waitcnt lgkmcnt(" #n ")" ::: "memory")
; #define PG8_BAR __builtin_amdgcn_s_barrier()
; #define PG8_SCHED __builtin_amdgcn_sched_barrier(0)
; template <class Epi, class Sched, bool ALIGN_EPI = false, bool SP2 = false>
; __device__ __forceinline__ void gemm_phase(PG8_LAS unsigned char* lds, const Gemm g, const Sched& S, const Epi& E) {
;     ...
;             PG8_LDA(At, 1, 1); PG8_STAGE(PG8_SB(1, 0), b3, voffB); PG8_STAGE(PG8_SB(1, 1), b3 + hstep, voffB); PG8_STAGE(PG8_SA(1, 0), a3, voffA);
;             PG8_WAIT_V(8); PG8_WAIT_L(0); PG8_BAR; PG8_MMA(1, 0, At, B0); PG8_MMA(1, 1, At, B1); PG8_BAR; PG8_SCHED;
;     ...
;         if constexpr (ALIGN_EPI) { if (wr == 0) PG8_BAR; }
	s_add_i32 s54, s70, s56
	v_lshl_add_u64 v[240:241], v[240:241], 0, s[14:15]
	s_mov_b32 m0, s54
	ds_read_b128 v[192:195], v197 offset:49152
	ds_read_b128 v[208:211], v197 offset:50176
	ds_read_b128 v[212:215], v197 offset:51200
	ds_read_b128 v[216:219], v197 offset:52224
	ds_read_b128 v[224:227], v197 offset:53248
	ds_read_b128 v[228:231], v197 offset:54272
	ds_read_b128 v[232:235], v197 offset:55296
	ds_read_b128 v[236:239], v197 offset:56320
	global_load_lds_dwordx4 v[240:241], off
	s_add_i32 m0, s54, 0x2000
	s_add_u32 s52, s52, 0x40080
	v_lshl_add_u64 v[240:241], v[242:243], 0, s[14:15]
	s_addc_u32 s53, s53, 0
	s_add_i32 s54, s71, s56
	global_load_lds_dwordx4 v[240:241], off
	v_lshl_add_u64 v[240:241], s[52:53], 0, v[180:181]
	s_mov_b32 m0, s54
	s_nop 0
	global_load_lds_dwordx4 v[240:241], off
	v_lshl_add_u64 v[240:241], s[52:53], 0, v[160:161]
	s_add_i32 m0, s54, 0x2000
	s_nop 0
	global_load_lds_dwordx4 v[240:241], off
	v_lshl_add_u64 v[240:241], v[244:245], 0, s[14:15]
	s_mov_b32 m0, s79
	s_nop 0
	global_load_lds_dwordx4 v[240:241], off
	v_lshl_add_u64 v[240:241], v[246:247], 0, s[14:15]
	s_mov_b32 m0, s80
	s_nop 0
	global_load_lds_dwordx4 v[240:241], off
	s_waitcnt vmcnt(8)
	s_waitcnt lgkmcnt(0)
	s_barrier
	s_setprio 1
	s_waitcnt lgkmcnt(0)
	v_mfma_f32_16x16x32_bf16 v[64:67], v[100:103], v[192:195], v[64:67]
	v_mfma_f32_16x16x32_bf16 v[60:63], v[124:127], v[192:195], v[60:63]
	v_mfma_f32_16x16x32_bf16 v[48:51], v[100:103], v[212:215], v[48:51]
	v_mfma_f32_16x16x32_bf16 v[44:47], v[124:127], v[212:215], v[44:47]
	v_mfma_f32_16x16x32_bf16 v[32:35], v[100:103], v[224:227], v[32:35]
	v_mfma_f32_16x16x32_bf16 v[28:31], v[124:127], v[224:227], v[28:31]
	v_mfma_f32_16x16x32_bf16 v[16:19], v[100:103], v[232:235], v[16:19]
	v_mfma_f32_16x16x32_bf16 v[12:15], v[124:127], v[232:235], v[12:15]
	v_mfma_f32_16x16x32_bf16 v[64:67], v[112:115], v[208:211], v[64:67]
	v_mfma_f32_16x16x32_bf16 v[60:63], v[136:139], v[208:211], v[60:63]
	v_mfma_f32_16x16x32_bf16 v[48:51], v[112:115], v[216:219], v[48:51]
	v_mfma_f32_16x16x32_bf16 v[44:47], v[136:139], v[216:219], v[44:47]
	v_mfma_f32_16x16x32_bf16 v[32:35], v[112:115], v[228:231], v[32:35]
	v_mfma_f32_16x16x32_bf16 v[28:31], v[136:139], v[228:231], v[28:31]
	v_mfma_f32_16x16x32_bf16 v[16:19], v[112:115], v[236:239], v[16:19]
	v_mfma_f32_16x16x32_bf16 v[12:15], v[136:139], v[236:239], v[12:15]
	v_mfma_f32_16x16x32_bf16 v[56:59], v[148:151], v[192:195], v[56:59]
	v_mfma_f32_16x16x32_bf16 v[52:55], v[156:159], v[192:195], v[52:55]
	v_mfma_f32_16x16x32_bf16 v[40:43], v[148:151], v[212:215], v[40:43]
	v_mfma_f32_16x16x32_bf16 v[36:39], v[156:159], v[212:215], v[36:39]
	v_mfma_f32_16x16x32_bf16 v[24:27], v[148:151], v[224:227], v[24:27]
	v_mfma_f32_16x16x32_bf16 v[20:23], v[156:159], v[224:227], v[20:23]
	v_mfma_f32_16x16x32_bf16 v[8:11], v[148:151], v[232:235], v[8:11]
	v_mfma_f32_16x16x32_bf16 v[4:7], v[156:159], v[232:235], v[4:7]
	v_mfma_f32_16x16x32_bf16 v[56:59], v[152:155], v[208:211], v[56:59]
	v_mfma_f32_16x16x32_bf16 v[52:55], v[188:191], v[208:211], v[52:55]
	v_mfma_f32_16x16x32_bf16 v[40:43], v[152:155], v[216:219], v[40:43]
	v_mfma_f32_16x16x32_bf16 v[36:39], v[188:191], v[216:219], v[36:39]
	v_mfma_f32_16x16x32_bf16 v[24:27], v[152:155], v[228:231], v[24:27]
	v_mfma_f32_16x16x32_bf16 v[20:23], v[188:191], v[228:231], v[20:23]
	v_mfma_f32_16x16x32_bf16 v[8:11], v[152:155], v[236:239], v[8:11]
	v_mfma_f32_16x16x32_bf16 v[4:7], v[188:191], v[236:239], v[4:7]
	s_setprio 0
	s_add_i32 s89, s89, 2
	s_add_u32 s50, s50, 0x100
	s_addc_u32 s51, s51, 0
	s_add_u32 s84, s84, 0x100
	s_addc_u32 s85, s85, 0
	s_cmp_gt_u32 s89, 13
	s_barrier
	s_cbranch_scc0 .LBB0_698
	s_and_b64 vcc, exec, s[36:37]
	s_cbranch_vccz .LBB0_701
	s_barrier

; #define PG8_STAGE(bufoff, gbase, voff) do { _Pragma("unroll") for (int _i = 0; _i < 2; ++_i) \
;         __builtin_amdgcn_global_load_lds((const unsigned*)((const char*)(gbase) + (voff)[_i]), (PG8_LAS unsigned*)(lds + (bufoff) + ldsw + _i * 8192), 16, 0, 0); } while (0)
; #define PG8_LDA(dst, b, h) do { _Pragma("unroll") for (int m = 0; m < 4; ++m) _Pragma("unroll") for (int k = 0; k < 2; ++k) dst[m][k] = *(const PG8_LAS bf16x8*)(lds + PG8_SA(b, h) + aoff + m * 2048 + k * 1024); } while (0)
; #define PG8_LDB(dst, b, h) do { _Pragma("unroll") for (int n = 0; n < 2; ++n) _Pragma("unroll") for (int k = 0; k < 2; ++k) dst[n][k] = *(const PG8_LAS bf16x8*)(lds + PG8_SB(b, h) + boff + n * 2048 + k * 1024); } while (0)
; #define PG8_MMA(ai, bj, At, Bt) do { __builtin_amdgcn_s_setprio(1); _Pragma("unroll") for (int m = 0; m < 4; ++m) _Pragma("unroll") for (int n = 0; n < 2; ++n) _Pragma("unroll") for (int k = 0; k < 2; ++k) \
;         acc[ai][bj][m][n] = __builtin_amdgcn_mfma_f32_16x16x32_bf16(Bt[n][k], At[m][k], acc[ai][bj][m][n], 0, 0, 0); __builtin_amdgcn_s_setprio(0); } while (0)
; #define PG8_WAIT_V(n) asm volatile("s_waitcnt vmcnt(" #n ")" ::: "memory")
; #define PG8_WAIT_L(n) asm volatile("s_waitcnt lgkmcnt(" #n ")" ::: "memory")
; template <class Epi, class Sched, bool ALIGN_EPI = false, bool SP2 = false>
; __device__ __forceinline__ void gemm_phase(PG8_LAS unsigned char* lds, const Gemm g, const Sched& S, const Epi& E) {
;     ...
;             const bool last = (t == nt - 2);
;             const char* a1 = cA + (size_t)(t + 1) * kstep;
;             const char* a2 = last ? nA : cA + (size_t)(t + 2) * kstep; const char* b2 = last ? nB : cB + (size_t)(t + 2) * kstep;
;             const char* a3 = a2 + kstep; const char* b3 = b2 + kstep;
;             if (last && has_next) S.a_ready(nxt);
;             if constexpr (SP2) {
;             PG8_LDB(B0, 0, 0); PG8_LDB(B1, 0, 1); PG8_SCHED; PG8_LDA(At, 0, 0); PG8_STAGE(PG8_SA(1, 1), a1 + hstep, voffA);
;             PG8_WAIT_V(8); PG8_WAIT_L(0); PG8_BAR; PG8_MMA(0, 0, At, B0); PG8_MMA(0, 1, At, B1); PG8_BAR; PG8_SCHED;
;             PG8_LDA(At, 0, 1); PG8_STAGE(PG8_SB(0, 0), b2, voffB); PG8_STAGE(PG8_SB(0, 1), b2 + hstep, voffB); PG8_STAGE(PG8_SA(0, 0), a2, voffA);
;             PG8_WAIT_V(8); PG8_WAIT_L(0); PG8_BAR; PG8_MMA(1, 0, At, B0); PG8_MMA(1, 1, At, B1); PG8_BAR; PG8_SCHED;
.LBB0_770:
	s_add_u32 s40, s54, 0xfffc0080
	s_addc_u32 s41, s55, -1
	s_add_i32 s70, 0, 0x10000
	s_cmp_eq_u32 vcc_lo, 12
	s_cselect_b32 s79, s6, s41
	s_cselect_b32 s78, s7, s40
	s_cselect_b32 s61, s47, s96
	s_cselect_b32 s60, s49, s91
	s_add_i32 s71, 0, 0x14000
	v_add_u32_e32 v158, s70, v151
	v_add_u32_e32 v162, s71, v151
	ds_read_b128 v[132:135], v158
	ds_read_b128 v[146:149], v158 offset:1024
	ds_read_b128 v[154:157], v158 offset:2048
	ds_read_b128 v[158:161], v158 offset:3072
	ds_read_b128 v[180:183], v162
	ds_read_b128 v[184:187], v162 offset:1024
	ds_read_b128 v[188:191], v162 offset:2048
	ds_read_b128 v[192:195], v162 offset:3072
	v_lshl_add_u64 v[162:163], s[54:55], 0, v[142:143]
	s_add_i32 m0, s81, 0xc000
	ds_read_b128 v[208:211], v153
	ds_read_b128 v[212:215], v153 offset:1024
	ds_read_b128 v[216:219], v153 offset:2048
	ds_read_b128 v[224:227], v153 offset:3072
	ds_read_b128 v[228:231], v153 offset:4096
	ds_read_b128 v[232:235], v153 offset:5120
	ds_read_b128 v[236:239], v153 offset:6144
	ds_read_b128 v[240:243], v153 offset:7168
	global_load_lds_dwordx4 v[162:163], off
	v_lshl_add_u64 v[162:163], s[54:55], 0, v[144:145]
	s_add_i32 m0, s81, 0xe000
	s_nop 0
	global_load_lds_dwordx4 v[162:163], off
	s_waitcnt vmcnt(8)
	s_waitcnt lgkmcnt(0)
	s_barrier
	s_setprio 1
	s_waitcnt lgkmcnt(0)
	v_mfma_f32_16x16x32_bf16 v[128:131], v[132:135], v[208:211], v[128:131]
	v_mfma_f32_16x16x32_bf16 v[124:127], v[154:157], v[208:211], v[124:127]
	v_mfma_f32_16x16x32_bf16 v[116:119], v[132:135], v[216:219], v[116:119]
	v_mfma_f32_16x16x32_bf16 v[108:111], v[154:157], v[216:219], v[108:111]
	v_mfma_f32_16x16x32_bf16 v[100:103], v[132:135], v[228:231], v[100:103]
	v_mfma_f32_16x16x32_bf16 v[92:95], v[154:157], v[228:231], v[92:95]
	v_mfma_f32_16x16x32_bf16 v[84:87], v[132:135], v[236:239], v[84:87]
	v_mfma_f32_16x16x32_bf16 v[76:79], v[154:157], v[236:239], v[76:79]
	v_mfma_f32_16x16x32_bf16 v[128:131], v[146:149], v[212:215], v[128:131]
	v_mfma_f32_16x16x32_bf16 v[124:127], v[158:161], v[212:215], v[124:127]
	v_mfma_f32_16x16x32_bf16 v[116:119], v[146:149], v[224:227], v[116:119]
	v_mfma_f32_16x16x32_bf16 v[108:111], v[158:161], v[224:227], v[108:111]
	v_mfma_f32_16x16x32_bf16 v[100:103], v[146:149], v[232:235], v[100:103]
	v_mfma_f32_16x16x32_bf16 v[92:95], v[158:161], v[232:235], v[92:95]
	v_mfma_f32_16x16x32_bf16 v[84:87], v[146:149], v[240:243], v[84:87]
	v_mfma_f32_16x16x32_bf16 v[76:79], v[158:161], v[240:243], v[76:79]
	v_mfma_f32_16x16x32_bf16 v[120:123], v[180:183], v[208:211], v[120:123]
	v_mfma_f32_16x16x32_bf16 v[112:115], v[188:191], v[208:211], v[112:115]
	v_mfma_f32_16x16x32_bf16 v[104:107], v[180:183], v[216:219], v[104:107]
	v_mfma_f32_16x16x32_bf16 v[96:99], v[188:191], v[216:219], v[96:99]
	v_mfma_f32_16x16x32_bf16 v[88:91], v[180:183], v[228:231], v[88:91]
	v_mfma_f32_16x16x32_bf16 v[80:83], v[188:191], v[228:231], v[80:83]
	v_mfma_f32_16x16x32_bf16 v[72:75], v[180:183], v[236:239], v[72:75]
	v_mfma_f32_16x16x32_bf16 v[68:71], v[188:191], v[236:239], v[68:71]
	v_mfma_f32_16x16x32_bf16 v[120:123], v[184:187], v[212:215], v[120:123]
	v_mfma_f32_16x16x32_bf16 v[112:115], v[192:195], v[212:215], v[112:115]
	v_mfma_f32_16x16x32_bf16 v[104:107], v[184:187], v[224:227], v[104:107]
	v_mfma_f32_16x16x32_bf16 v[96:99], v[192:195], v[224:227], v[96:99]
	v_mfma_f32_16x16x32_bf16 v[88:91], v[184:187], v[232:235], v[88:91]
	v_mfma_f32_16x16x32_bf16 v[80:83], v[192:195], v[232:235], v[80:83]
	v_mfma_f32_16x16x32_bf16 v[72:75], v[184:187], v[240:243], v[72:75]
	v_mfma_f32_16x16x32_bf16 v[68:71], v[192:195], v[240:243], v[68:71]
	s_setprio 0
	s_barrier
	s_add_i32 s40, s70, s80
	v_lshl_add_u64 v[162:163], s[60:61], 0, v[2:3]
	s_mov_b32 m0, s40
	ds_read_b128 v[208:211], v153 offset:16384
	ds_read_b128 v[212:215], v153 offset:17408
	ds_read_b128 v[216:219], v153 offset:18432
	ds_read_b128 v[224:227], v153 offset:19456
	ds_read_b128 v[228:231], v153 offset:20480
	ds_read_b128 v[232:235], v153 offset:21504
	ds_read_b128 v[236:239], v153 offset:22528
	ds_read_b128 v[240:243], v153 offset:23552
	global_load_lds_dwordx4 v[162:163], off
	s_add_i32 m0, s40, 0x2000
	s_add_u32 s40, s60, 0x40000
	v_lshl_add_u64 v[196:197], s[60:61], 0, v[136:137]
	s_addc_u32 s41, s61, 0
	s_add_i32 s70, s71, s80
	global_load_lds_dwordx4 v[196:197], off
	v_lshl_add_u64 v[244:245], s[40:41], 0, v[2:3]
	s_mov_b32 m0, s70
	v_lshl_add_u64 v[246:247], s[78:79], 0, v[138:139]
	global_load_lds_dwordx4 v[244:245], off
	v_lshl_add_u64 v[244:245], s[40:41], 0, v[136:137]
	s_add_i32 m0, s70, 0x2000
	s_nop 0
	global_load_lds_dwordx4 v[244:245], off
	v_lshl_add_u64 v[244:245], s[78:79], 0, v[140:141]
	s_mov_b32 m0, s81
	s_nop 0
	global_load_lds_dwordx4 v[244:245], off
	s_mov_b32 m0, s82
	s_nop 0
	global_load_lds_dwordx4 v[246:247], off
	s_waitcnt vmcnt(8)
	s_waitcnt lgkmcnt(0)
	s_barrier
; #define PG8_STAGE(bufoff, gbase, voff) do { _Pragma("unroll") for (int _i = 0; _i < 2; ++_i) \
;         __builtin_amdgcn_global_load_lds((const unsigned*)((const char*)(gbase) + (voff)[_i]), (PG8_LAS unsigned*)(lds + (bufoff) + ldsw + _i * 8192), 16, 0, 0); } while (0)
; #define PG8_LDA(dst, b, h) do { _Pragma("unroll") for (int m = 0; m < 4; ++m) _Pragma("unroll") for (int k = 0; k < 2; ++k) dst[m][k] = *(const PG8_LAS bf16x8*)(lds + PG8_SA(b, h) + aoff + m * 2048 + k * 1024); } while (0)
; #define PG8_LDB(dst, b, h) do { _Pragma("unroll") for (int n = 0; n < 2; ++n) _Pragma("unroll") for (int k = 0; k < 2; ++k) dst[n][k] = *(const PG8_LAS bf16x8*)(lds + PG8_SB(b, h) + boff + n * 2048 + k * 1024); } while (0)
; #define PG8_MMA(ai, bj, At, Bt) do { __builtin_amdgcn_s_setprio(1); _Pragma("unroll") for (int m = 0; m < 4; ++m) _Pragma("unroll") for (int n = 0; n < 2; ++n) _Pragma("unroll") for (int k = 0; k < 2; ++k) \
;         acc[ai][bj][m][n] = __builtin_amdgcn_mfma_f32_16x16x32_bf16(Bt[n][k], At[m][k], acc[ai][bj][m][n], 0, 0, 0); __builtin_amdgcn_s_setprio(0); } while (0)
; #define PG8_WAIT_V(n) asm volatile("s_waitcnt vmcnt(" #n ")" ::: "memory")
; #define PG8_WAIT_L(n) asm volatile("s_waitcnt lgkmcnt(" #n ")" ::: "memory")
; #define PG8_BAR __builtin_amdgcn_s_barrier()
; #define PG8_SCHED __builtin_amdgcn_sched_barrier(0)
; template <class Epi, class Sched, bool ALIGN_EPI = false, bool SP2 = false>
; __device__ __forceinline__ void gemm_phase(PG8_LAS unsigned char* lds, const Gemm g, const Sched& S, const Epi& E) {
;     ...
;             PG8_WAIT_V(8); PG8_WAIT_L(0); PG8_BAR; PG8_MMA(1, 0, At, B0); PG8_MMA(1, 1, At, B1); PG8_BAR; PG8_SCHED;
;             PG8_LDB(B0, 1, 0); PG8_LDB(B1, 1, 1); PG8_SCHED; PG8_LDA(At, 1, 0); PG8_STAGE(PG8_SA(0, 1), a2 + hstep, voffA);
;             PG8_WAIT_V(8); PG8_WAIT_L(0); PG8_BAR; PG8_MMA(0, 0, At, B0); PG8_MMA(0, 1, At, B1); PG8_BAR; PG8_SCHED;
	s_setprio 1
	s_waitcnt lgkmcnt(0)
	v_mfma_f32_16x16x32_bf16 v[64:67], v[132:135], v[208:211], v[64:67]
	v_mfma_f32_16x16x32_bf16 v[60:63], v[154:157], v[208:211], v[60:63]
	v_mfma_f32_16x16x32_bf16 v[52:55], v[132:135], v[216:219], v[52:55]
	v_mfma_f32_16x16x32_bf16 v[44:47], v[154:157], v[216:219], v[44:47]
	v_mfma_f32_16x16x32_bf16 v[36:39], v[132:135], v[228:231], v[36:39]
	v_mfma_f32_16x16x32_bf16 v[28:31], v[154:157], v[228:231], v[28:31]
	v_mfma_f32_16x16x32_bf16 v[20:23], v[132:135], v[236:239], v[20:23]
	v_mfma_f32_16x16x32_bf16 v[12:15], v[154:157], v[236:239], v[12:15]
	v_mfma_f32_16x16x32_bf16 v[64:67], v[146:149], v[212:215], v[64:67]
	v_mfma_f32_16x16x32_bf16 v[60:63], v[158:161], v[212:215], v[60:63]
	v_mfma_f32_16x16x32_bf16 v[52:55], v[146:149], v[224:227], v[52:55]
	v_mfma_f32_16x16x32_bf16 v[44:47], v[158:161], v[224:227], v[44:47]
	v_mfma_f32_16x16x32_bf16 v[36:39], v[146:149], v[232:235], v[36:39]
	v_mfma_f32_16x16x32_bf16 v[28:31], v[158:161], v[232:235], v[28:31]
	v_mfma_f32_16x16x32_bf16 v[20:23], v[146:149], v[240:243], v[20:23]
	v_mfma_f32_16x16x32_bf16 v[12:15], v[158:161], v[240:243], v[12:15]
	v_mfma_f32_16x16x32_bf16 v[56:59], v[180:183], v[208:211], v[56:59]
	v_mfma_f32_16x16x32_bf16 v[48:51], v[188:191], v[208:211], v[48:51]
	v_mfma_f32_16x16x32_bf16 v[40:43], v[180:183], v[216:219], v[40:43]
	v_mfma_f32_16x16x32_bf16 v[32:35], v[188:191], v[216:219], v[32:35]
	v_mfma_f32_16x16x32_bf16 v[24:27], v[180:183], v[228:231], v[24:27]
	v_mfma_f32_16x16x32_bf16 v[16:19], v[188:191], v[228:231], v[16:19]
	v_mfma_f32_16x16x32_bf16 v[8:11], v[180:183], v[236:239], v[8:11]
	v_mfma_f32_16x16x32_bf16 v[4:7], v[188:191], v[236:239], v[4:7]
	v_mfma_f32_16x16x32_bf16 v[56:59], v[184:187], v[212:215], v[56:59]
	v_mfma_f32_16x16x32_bf16 v[48:51], v[192:195], v[212:215], v[48:51]
	v_mfma_f32_16x16x32_bf16 v[40:43], v[184:187], v[224:227], v[40:43]
	v_mfma_f32_16x16x32_bf16 v[32:35], v[192:195], v[224:227], v[32:35]
	v_mfma_f32_16x16x32_bf16 v[24:27], v[184:187], v[232:235], v[24:27]
	v_mfma_f32_16x16x32_bf16 v[16:19], v[192:195], v[232:235], v[16:19]
	v_mfma_f32_16x16x32_bf16 v[8:11], v[184:187], v[240:243], v[8:11]
	v_mfma_f32_16x16x32_bf16 v[4:7], v[192:195], v[240:243], v[4:7]
	s_setprio 0
	s_barrier
	s_add_i32 s70, 0, 0x18000
	s_add_i32 s71, 0, 0x1c000
	v_add_u32_e32 v158, s70, v151
	v_add_u32_e32 v167, s71, v151
	ds_read_b128 v[132:135], v158
	ds_read_b128 v[146:149], v158 offset:1024
	ds_read_b128 v[154:157], v158 offset:2048
	ds_read_b128 v[158:161], v158 offset:3072
	ds_read_b128 v[180:183], v167
	ds_read_b128 v[184:187], v167 offset:1024
	ds_read_b128 v[188:191], v167 offset:2048
	ds_read_b128 v[192:195], v167 offset:3072
	s_add_u32 s40, s78, 0x40000
	s_addc_u32 s41, s79, 0
	s_mov_b32 m0, s83
	v_lshl_add_u64 v[248:249], s[40:41], 0, v[140:141]
	ds_read_b128 v[208:211], v153 offset:32768
	ds_read_b128 v[212:215], v153 offset:33792
	ds_read_b128 v[216:219], v153 offset:34816
	ds_read_b128 v[224:227], v153 offset:35840
	ds_read_b128 v[228:231], v153 offset:36864
	ds_read_b128 v[232:235], v153 offset:37888
	ds_read_b128 v[236:239], v153 offset:38912
	ds_read_b128 v[240:243], v153 offset:39936
	global_load_lds_dwordx4 v[248:249], off
	v_lshl_add_u64 v[248:249], s[40:41], 0, v[138:139]
	s_mov_b32 m0, s84
	s_nop 0
	global_load_lds_dwordx4 v[248:249], off
	s_waitcnt vmcnt(8)
	s_waitcnt lgkmcnt(0)
	s_barrier
	s_setprio 1
	s_waitcnt lgkmcnt(0)
	v_mfma_f32_16x16x32_bf16 v[128:131], v[132:135], v[208:211], v[128:131]
	v_mfma_f32_16x16x32_bf16 v[124:127], v[154:157], v[208:211], v[124:127]
	v_mfma_f32_16x16x32_bf16 v[116:119], v[132:135], v[216:219], v[116:119]
	v_mfma_f32_16x16x32_bf16 v[108:111], v[154:157], v[216:219], v[108:111]
	v_mfma_f32_16x16x32_bf16 v[100:103], v[132:135], v[228:231], v[100:103]
	v_mfma_f32_16x16x32_bf16 v[92:95], v[154:157], v[228:231], v[92:95]
	v_mfma_f32_16x16x32_bf16 v[84:87], v[132:135], v[236:239], v[84:87]
	v_mfma_f32_16x16x32_bf16 v[76:79], v[154:157], v[236:239], v[76:79]
	v_mfma_f32_16x16x32_bf16 v[128:131], v[146:149], v[212:215], v[128:131]
	v_mfma_f32_16x16x32_bf16 v[124:127], v[158:161], v[212:215], v[124:127]
	v_mfma_f32_16x16x32_bf16 v[116:119], v[146:149], v[224:227], v[116:119]
	v_mfma_f32_16x16x32_bf16 v[108:111], v[158:161], v[224:227], v[108:111]
	v_mfma_f32_16x16x32_bf16 v[100:103], v[146:149], v[232:235], v[100:103]
	v_mfma_f32_16x16x32_bf16 v[92:95], v[158:161], v[232:235], v[92:95]
	v_mfma_f32_16x16x32_bf16 v[84:87], v[146:149], v[240:243], v[84:87]
	v_mfma_f32_16x16x32_bf16 v[76:79], v[158:161], v[240:243], v[76:79]
	v_mfma_f32_16x16x32_bf16 v[120:123], v[180:183], v[208:211], v[120:123]
	v_mfma_f32_16x16x32_bf16 v[112:115], v[188:191], v[208:211], v[112:115]
	v_mfma_f32_16x16x32_bf16 v[104:107], v[180:183], v[216:219], v[104:107]
	v_mfma_f32_16x16x32_bf16 v[96:99], v[188:191], v[216:219], v[96:99]
	v_mfma_f32_16x16x32_bf16 v[88:91], v[180:183], v[228:231], v[88:91]
	v_mfma_f32_16x16x32_bf16 v[80:83], v[188:191], v[228:231], v[80:83]
	v_mfma_f32_16x16x32_bf16 v[72:75], v[180:183], v[236:239], v[72:75]
	v_mfma_f32_16x16x32_bf16 v[68:71], v[188:191], v[236:239], v[68:71]
	v_mfma_f32_16x16x32_bf16 v[120:123], v[184:187], v[212:215], v[120:123]
	v_mfma_f32_16x16x32_bf16 v[112:115], v[192:195], v[212:215], v[112:115]
	v_mfma_f32_16x16x32_bf16 v[104:107], v[184:187], v[224:227], v[104:107]
	v_mfma_f32_16x16x32_bf16 v[96:99], v[192:195], v[224:227], v[96:99]
	v_mfma_f32_16x16x32_bf16 v[88:91], v[184:187], v[232:235], v[88:91]
	v_mfma_f32_16x16x32_bf16 v[80:83], v[192:195], v[232:235], v[80:83]
	v_mfma_f32_16x16x32_bf16 v[72:75], v[184:187], v[240:243], v[72:75]
	v_mfma_f32_16x16x32_bf16 v[68:71], v[192:195], v[240:243], v[68:71]
	s_setprio 0
	s_barrier
; #define PG8_STAGE(bufoff, gbase, voff) do { _Pragma("unroll") for (int _i = 0; _i < 2; ++_i) \
;         __builtin_amdgcn_global_load_lds((const unsigned*)((const char*)(gbase) + (voff)[_i]), (PG8_LAS unsigned*)(lds + (bufoff) + ldsw + _i * 8192), 16, 0, 0); } while (0)
; #define PG8_LDA(dst, b, h) do { _Pragma("unroll") for (int m = 0; m < 4; ++m) _Pragma("unroll") for (int k = 0; k < 2; ++k) dst[m][k] = *(const PG8_LAS bf16x8*)(lds + PG8_SA(b, h) + aoff + m * 2048 + k * 1024); } while (0)
; #define PG8_MMA(ai, bj, At, Bt) do { __builtin_amdgcn_s_setprio(1); _Pragma("unroll") for (int m = 0; m < 4; ++m) _Pragma("unroll") for (int n = 0; n < 2; ++n) _Pragma("unroll") for (int k = 0; k < 2; ++k) \
;         acc[ai][bj][m][n] = __builtin_amdgcn_mfma_f32_16x16x32_bf16(Bt[n][k], At[m][k], acc[ai][bj][m][n], 0, 0, 0); __builtin_amdgcn_s_setprio(0); } while (0)
; #define PG8_WAIT_V(n) asm volatile("s_waitcnt vmcnt(" #n ")" ::: "memory")
; #define PG8_WAIT_L(n) asm volatile("s_waitcnt lgkmcnt(" #n ")" ::: "memory")
; #define PG8_BAR __builtin_amdgcn_s_barrier()
; #define PG8_SCHED __builtin_amdgcn_sched_barrier(0)
; template <class Epi, class Sched, bool ALIGN_EPI = false, bool SP2 = false>
; __device__ __forceinline__ void gemm_phase(PG8_LAS unsigned char* lds, const Gemm g, const Sched& S, const Epi& E) {
;     ...
;             PG8_LDA(At, 1, 1); PG8_STAGE(PG8_SB(1, 0), b3, voffB); PG8_STAGE(PG8_SB(1, 1), b3 + hstep, voffB); PG8_STAGE(PG8_SA(1, 0), a3, voffA);
;             PG8_WAIT_V(8); PG8_WAIT_L(0); PG8_BAR; PG8_MMA(1, 0, At, B0); PG8_MMA(1, 1, At, B1); PG8_BAR; PG8_SCHED;
;     ...
;         if constexpr (ALIGN_EPI) { if (wr == 0) PG8_BAR; }
	s_add_i32 s40, s70, s80
	v_lshl_add_u64 v[162:163], v[162:163], 0, s[14:15]
	s_mov_b32 m0, s40
	ds_read_b128 v[208:211], v153 offset:49152
	ds_read_b128 v[212:215], v153 offset:50176
	ds_read_b128 v[216:219], v153 offset:51200
	ds_read_b128 v[224:227], v153 offset:52224
	ds_read_b128 v[228:231], v153 offset:53248
	ds_read_b128 v[232:235], v153 offset:54272
	ds_read_b128 v[236:239], v153 offset:55296
	ds_read_b128 v[240:243], v153 offset:56320
	global_load_lds_dwordx4 v[162:163], off
	s_add_i32 m0, s40, 0x2000
	s_add_u32 s40, s60, 0x40080
	v_lshl_add_u64 v[162:163], v[196:197], 0, s[14:15]
	s_addc_u32 s41, s61, 0
	s_add_i32 s60, s71, s80
	global_load_lds_dwordx4 v[162:163], off
	v_lshl_add_u64 v[162:163], s[40:41], 0, v[2:3]
	s_mov_b32 m0, s60
	s_nop 0
	global_load_lds_dwordx4 v[162:163], off
	v_lshl_add_u64 v[162:163], s[40:41], 0, v[136:137]
	s_add_i32 m0, s60, 0x2000
	s_nop 0
	global_load_lds_dwordx4 v[162:163], off
	v_lshl_add_u64 v[162:163], v[244:245], 0, s[14:15]
	s_mov_b32 m0, s28
	s_nop 0
	global_load_lds_dwordx4 v[162:163], off
	v_lshl_add_u64 v[162:163], v[246:247], 0, s[14:15]
	s_mov_b32 m0, s29
	s_nop 0
	global_load_lds_dwordx4 v[162:163], off
	s_waitcnt vmcnt(8)
	s_waitcnt lgkmcnt(0)
	s_barrier
	s_setprio 1
	s_waitcnt lgkmcnt(0)
	v_mfma_f32_16x16x32_bf16 v[64:67], v[132:135], v[208:211], v[64:67]
	v_mfma_f32_16x16x32_bf16 v[60:63], v[154:157], v[208:211], v[60:63]
	v_mfma_f32_16x16x32_bf16 v[52:55], v[132:135], v[216:219], v[52:55]
	v_mfma_f32_16x16x32_bf16 v[44:47], v[154:157], v[216:219], v[44:47]
	v_mfma_f32_16x16x32_bf16 v[36:39], v[132:135], v[228:231], v[36:39]
	v_mfma_f32_16x16x32_bf16 v[28:31], v[154:157], v[228:231], v[28:31]
	v_mfma_f32_16x16x32_bf16 v[20:23], v[132:135], v[236:239], v[20:23]
	v_mfma_f32_16x16x32_bf16 v[12:15], v[154:157], v[236:239], v[12:15]
	v_mfma_f32_16x16x32_bf16 v[64:67], v[146:149], v[212:215], v[64:67]
	v_mfma_f32_16x16x32_bf16 v[60:63], v[158:161], v[212:215], v[60:63]
	v_mfma_f32_16x16x32_bf16 v[52:55], v[146:149], v[224:227], v[52:55]
	v_mfma_f32_16x16x32_bf16 v[44:47], v[158:161], v[224:227], v[44:47]
	v_mfma_f32_16x16x32_bf16 v[36:39], v[146:149], v[232:235], v[36:39]
	v_mfma_f32_16x16x32_bf16 v[28:31], v[158:161], v[232:235], v[28:31]
	v_mfma_f32_16x16x32_bf16 v[20:23], v[146:149], v[240:243], v[20:23]
	v_mfma_f32_16x16x32_bf16 v[12:15], v[158:161], v[240:243], v[12:15]
	v_mfma_f32_16x16x32_bf16 v[56:59], v[180:183], v[208:211], v[56:59]
	v_mfma_f32_16x16x32_bf16 v[48:51], v[188:191], v[208:211], v[48:51]
	v_mfma_f32_16x16x32_bf16 v[40:43], v[180:183], v[216:219], v[40:43]
	v_mfma_f32_16x16x32_bf16 v[32:35], v[188:191], v[216:219], v[32:35]
	v_mfma_f32_16x16x32_bf16 v[24:27], v[180:183], v[228:231], v[24:27]
	v_mfma_f32_16x16x32_bf16 v[16:19], v[188:191], v[228:231], v[16:19]
	v_mfma_f32_16x16x32_bf16 v[8:11], v[180:183], v[236:239], v[8:11]
	v_mfma_f32_16x16x32_bf16 v[4:7], v[188:191], v[236:239], v[4:7]
	v_mfma_f32_16x16x32_bf16 v[56:59], v[184:187], v[212:215], v[56:59]
	v_mfma_f32_16x16x32_bf16 v[48:51], v[192:195], v[212:215], v[48:51]
	v_mfma_f32_16x16x32_bf16 v[40:43], v[184:187], v[224:227], v[40:43]
	v_mfma_f32_16x16x32_bf16 v[32:35], v[192:195], v[224:227], v[32:35]
	v_mfma_f32_16x16x32_bf16 v[24:27], v[184:187], v[232:235], v[24:27]
	v_mfma_f32_16x16x32_bf16 v[16:19], v[192:195], v[232:235], v[16:19]
	v_mfma_f32_16x16x32_bf16 v[8:11], v[184:187], v[240:243], v[8:11]
	v_mfma_f32_16x16x32_bf16 v[4:7], v[192:195], v[240:243], v[4:7]
	s_setprio 0
	s_barrier
	s_add_i32 vcc_lo, vcc_lo, 2
	s_add_u32 s54, s54, 0x100
	s_addc_u32 s55, s55, 0
	s_add_u32 s91, s91, 0x100
	s_addc_u32 s96, s96, 0
	s_cmp_gt_u32 vcc_lo, 13
	s_cbranch_scc0 .LBB0_770
	s_and_b64 vcc, exec, s[44:45]
	s_cbranch_vccz .LBB0_773
	s_barrier

; #define PG8_STAGE(bufoff, gbase, voff) do { _Pragma("unroll") for (int _i = 0; _i < 2; ++_i) \
;         __builtin_amdgcn_global_load_lds((const unsigned*)((const char*)(gbase) + (voff)[_i]), (PG8_LAS unsigned*)(lds + (bufoff) + ldsw + _i * 8192), 16, 0, 0); } while (0)
; #define PG8_LDA(dst, b, h) do { _Pragma("unroll") for (int m = 0; m < 4; ++m) _Pragma("unroll") for (int k = 0; k < 2; ++k) dst[m][k] = *(const PG8_LAS bf16x8*)(lds + PG8_SA(b, h) + aoff + m * 2048 + k * 1024); } while (0)
; #define PG8_LDB(dst, b, h) do { _Pragma("unroll") for (int n = 0; n < 2; ++n) _Pragma("unroll") for (int k = 0; k < 2; ++k) dst[n][k] = *(const PG8_LAS bf16x8*)(lds + PG8_SB(b, h) + boff + n * 2048 + k * 1024); } while (0)
; #define PG8_MMA(ai, bj, At, Bt) do { __builtin_amdgcn_s_setprio(1); _Pragma("unroll") for (int m = 0; m < 4; ++m) _Pragma("unroll") for (int n = 0; n < 2; ++n) _Pragma("unroll") for (int k = 0; k < 2; ++k) \
;         acc[ai][bj][m][n] = __builtin_amdgcn_mfma_f32_16x16x32_bf16(Bt[n][k], At[m][k], acc[ai][bj][m][n], 0, 0, 0); __builtin_amdgcn_s_setprio(0); } while (0)
; #define PG8_WAIT_V(n) asm volatile("s_waitcnt vmcnt(" #n ")" ::: "memory")
; #define PG8_WAIT_L(n) asm volatile("s_waitcnt lgkmcnt(" #n ")" ::: "memory")
; template <class Epi, class Sched, bool ALIGN_EPI = false, bool SP2 = false>
; __device__ __forceinline__ void gemm_phase(PG8_LAS unsigned char* lds, const Gemm g, const Sched& S, const Epi& E) {
;     ...
;             const bool last = (t == nt - 2);
;             const char* a1 = cA + (size_t)(t + 1) * kstep;
;             const char* a2 = last ? nA : cA + (size_t)(t + 2) * kstep; const char* b2 = last ? nB : cB + (size_t)(t + 2) * kstep;
;             const char* a3 = a2 + kstep; const char* b3 = b2 + kstep;
;             if (last && has_next) S.a_ready(nxt);
;             if constexpr (SP2) {
;             PG8_LDB(B0, 0, 0); PG8_LDB(B1, 0, 1); PG8_SCHED; PG8_LDA(At, 0, 0); PG8_STAGE(PG8_SA(1, 1), a1 + hstep, voffA);
;             PG8_WAIT_V(8); PG8_WAIT_L(0); PG8_BAR; PG8_MMA(0, 0, At, B0); PG8_MMA(0, 1, At, B1); PG8_BAR; PG8_SCHED;
;             PG8_LDA(At, 0, 1); PG8_STAGE(PG8_SB(0, 0), b2, voffB); PG8_STAGE(PG8_SB(0, 1), b2 + hstep, voffB); PG8_STAGE(PG8_SA(0, 0), a2, voffA);
;             PG8_WAIT_V(8); PG8_WAIT_L(0); PG8_BAR; PG8_MMA(1, 0, At, B0); PG8_MMA(1, 1, At, B1); PG8_BAR; PG8_SCHED;
.LBB0_790:
	s_add_u32 s41, s60, 0xfffc0080
	s_addc_u32 s70, s61, -1
	s_add_i32 s71, 0, 0x10000
	s_cmp_eq_u32 s40, 12
	s_cselect_b32 s85, s6, s70
	s_cselect_b32 s84, s7, s41
	s_cselect_b32 s79, s49, vcc_hi
	s_cselect_b32 s78, s51, vcc_lo
	s_add_i32 s41, 0, 0x14000
	v_add_u32_e32 v144, s71, v168
	v_add_u32_e32 v160, s41, v168
	ds_read_b128 v[132:135], v144
	ds_read_b128 v[136:139], v144 offset:1024
	ds_read_b128 v[140:143], v144 offset:2048
	ds_read_b128 v[144:147], v144 offset:3072
	ds_read_b128 v[148:151], v160
	ds_read_b128 v[152:155], v160 offset:1024
	ds_read_b128 v[156:159], v160 offset:2048
	ds_read_b128 v[160:163], v160 offset:3072
	v_lshl_add_u64 v[218:219], s[60:61], 0, v[186:187]
	s_add_i32 m0, s81, 0xc000
	ds_read_b128 v[190:193], v209
	ds_read_b128 v[194:197], v209 offset:1024
	ds_read_b128 v[210:213], v209 offset:2048
	ds_read_b128 v[214:217], v209 offset:3072
	ds_read_b128 v[224:227], v209 offset:4096
	ds_read_b128 v[228:231], v209 offset:5120
	ds_read_b128 v[232:235], v209 offset:6144
	ds_read_b128 v[236:239], v209 offset:7168
	global_load_lds_dwordx4 v[218:219], off
	v_lshl_add_u64 v[218:219], s[60:61], 0, v[188:189]
	s_add_i32 m0, s81, 0xe000
	s_nop 0
	global_load_lds_dwordx4 v[218:219], off
	s_waitcnt vmcnt(8)
	s_waitcnt lgkmcnt(0)
	s_barrier
	s_setprio 1
	s_waitcnt lgkmcnt(0)
	v_mfma_f32_16x16x32_bf16 v[128:131], v[132:135], v[190:193], v[128:131]
	v_mfma_f32_16x16x32_bf16 v[124:127], v[140:143], v[190:193], v[124:127]
	v_mfma_f32_16x16x32_bf16 v[112:115], v[132:135], v[210:213], v[112:115]
	v_mfma_f32_16x16x32_bf16 v[108:111], v[140:143], v[210:213], v[108:111]
	v_mfma_f32_16x16x32_bf16 v[96:99], v[132:135], v[224:227], v[96:99]
	v_mfma_f32_16x16x32_bf16 v[92:95], v[140:143], v[224:227], v[92:95]
	v_mfma_f32_16x16x32_bf16 v[80:83], v[132:135], v[232:235], v[80:83]
	v_mfma_f32_16x16x32_bf16 v[76:79], v[140:143], v[232:235], v[76:79]
	v_mfma_f32_16x16x32_bf16 v[128:131], v[136:139], v[194:197], v[128:131]
	v_mfma_f32_16x16x32_bf16 v[124:127], v[144:147], v[194:197], v[124:127]
	v_mfma_f32_16x16x32_bf16 v[112:115], v[136:139], v[214:217], v[112:115]
	v_mfma_f32_16x16x32_bf16 v[108:111], v[144:147], v[214:217], v[108:111]
	v_mfma_f32_16x16x32_bf16 v[96:99], v[136:139], v[228:231], v[96:99]
	v_mfma_f32_16x16x32_bf16 v[92:95], v[144:147], v[228:231], v[92:95]
	v_mfma_f32_16x16x32_bf16 v[80:83], v[136:139], v[236:239], v[80:83]
	v_mfma_f32_16x16x32_bf16 v[76:79], v[144:147], v[236:239], v[76:79]
	v_mfma_f32_16x16x32_bf16 v[120:123], v[148:151], v[190:193], v[120:123]
	v_mfma_f32_16x16x32_bf16 v[116:119], v[156:159], v[190:193], v[116:119]
	v_mfma_f32_16x16x32_bf16 v[104:107], v[148:151], v[210:213], v[104:107]
	v_mfma_f32_16x16x32_bf16 v[100:103], v[156:159], v[210:213], v[100:103]
	v_mfma_f32_16x16x32_bf16 v[88:91], v[148:151], v[224:227], v[88:91]
	v_mfma_f32_16x16x32_bf16 v[84:87], v[156:159], v[224:227], v[84:87]
	v_mfma_f32_16x16x32_bf16 v[72:75], v[148:151], v[232:235], v[72:75]
	v_mfma_f32_16x16x32_bf16 v[68:71], v[156:159], v[232:235], v[68:71]
	v_mfma_f32_16x16x32_bf16 v[120:123], v[152:155], v[194:197], v[120:123]
	v_mfma_f32_16x16x32_bf16 v[116:119], v[160:163], v[194:197], v[116:119]
	v_mfma_f32_16x16x32_bf16 v[104:107], v[152:155], v[214:217], v[104:107]
	v_mfma_f32_16x16x32_bf16 v[100:103], v[160:163], v[214:217], v[100:103]
	v_mfma_f32_16x16x32_bf16 v[88:91], v[152:155], v[228:231], v[88:91]
	v_mfma_f32_16x16x32_bf16 v[84:87], v[160:163], v[228:231], v[84:87]
	v_mfma_f32_16x16x32_bf16 v[72:75], v[152:155], v[236:239], v[72:75]
	v_mfma_f32_16x16x32_bf16 v[68:71], v[160:163], v[236:239], v[68:71]
	s_setprio 0
	s_barrier
	s_add_i32 s70, s71, s80
	v_lshl_add_u64 v[218:219], s[78:79], 0, v[2:3]
	s_mov_b32 m0, s70
	ds_read_b128 v[190:193], v209 offset:16384
	ds_read_b128 v[194:197], v209 offset:17408
	ds_read_b128 v[210:213], v209 offset:18432
	ds_read_b128 v[214:217], v209 offset:19456
	ds_read_b128 v[224:227], v209 offset:20480
	ds_read_b128 v[228:231], v209 offset:21504
	ds_read_b128 v[232:235], v209 offset:22528
	ds_read_b128 v[236:239], v209 offset:23552
	global_load_lds_dwordx4 v[218:219], off
	s_add_i32 m0, s70, 0x2000
	s_add_u32 s70, s78, 0x40000
	v_lshl_add_u64 v[240:241], s[78:79], 0, v[180:181]
	s_addc_u32 s71, s79, 0
	s_add_i32 s41, s41, s80
	global_load_lds_dwordx4 v[240:241], off
	v_lshl_add_u64 v[242:243], s[70:71], 0, v[2:3]
	s_mov_b32 m0, s41
	v_lshl_add_u64 v[244:245], s[84:85], 0, v[182:183]
	global_load_lds_dwordx4 v[242:243], off
	v_lshl_add_u64 v[242:243], s[70:71], 0, v[180:181]
	s_add_i32 m0, s41, 0x2000
	s_nop 0
	global_load_lds_dwordx4 v[242:243], off
	v_lshl_add_u64 v[242:243], s[84:85], 0, v[184:185]
	s_mov_b32 m0, s81
	s_nop 0
	global_load_lds_dwordx4 v[242:243], off
	s_mov_b32 m0, s82
	s_nop 0
	global_load_lds_dwordx4 v[244:245], off
	s_waitcnt vmcnt(8)
	s_waitcnt lgkmcnt(0)
	s_barrier
; #define PG8_STAGE(bufoff, gbase, voff) do { _Pragma("unroll") for (int _i = 0; _i < 2; ++_i) \
;         __builtin_amdgcn_global_load_lds((const unsigned*)((const char*)(gbase) + (voff)[_i]), (PG8_LAS unsigned*)(lds + (bufoff) + ldsw + _i * 8192), 16, 0, 0); } while (0)
; #define PG8_LDA(dst, b, h) do { _Pragma("unroll") for (int m = 0; m < 4; ++m) _Pragma("unroll") for (int k = 0; k < 2; ++k) dst[m][k] = *(const PG8_LAS bf16x8*)(lds + PG8_SA(b, h) + aoff + m * 2048 + k * 1024); } while (0)
; #define PG8_LDB(dst, b, h) do { _Pragma("unroll") for (int n = 0; n < 2; ++n) _Pragma("unroll") for (int k = 0; k < 2; ++k) dst[n][k] = *(const PG8_LAS bf16x8*)(lds + PG8_SB(b, h) + boff + n * 2048 + k * 1024); } while (0)
; #define PG8_MMA(ai, bj, At, Bt) do { __builtin_amdgcn_s_setprio(1); _Pragma("unroll") for (int m = 0; m < 4; ++m) _Pragma("unroll") for (int n = 0; n < 2; ++n) _Pragma("unroll") for (int k = 0; k < 2; ++k) \
;         acc[ai][bj][m][n] = __builtin_amdgcn_mfma_f32_16x16x32_bf16(Bt[n][k], At[m][k], acc[ai][bj][m][n], 0, 0, 0); __builtin_amdgcn_s_setprio(0); } while (0)
; #define PG8_WAIT_V(n) asm volatile("s_waitcnt vmcnt(" #n ")" ::: "memory")
; #define PG8_WAIT_L(n) asm volatile("s_waitcnt lgkmcnt(" #n ")" ::: "memory")
; #define PG8_BAR __builtin_amdgcn_s_barrier()
; #define PG8_SCHED __builtin_amdgcn_sched_barrier(0)
; template <class Epi, class Sched, bool ALIGN_EPI = false, bool SP2 = false>
; __device__ __forceinline__ void gemm_phase(PG8_LAS unsigned char* lds, const Gemm g, const Sched& S, const Epi& E) {
;     ...
;             PG8_WAIT_V(8); PG8_WAIT_L(0); PG8_BAR; PG8_MMA(1, 0, At, B0); PG8_MMA(1, 1, At, B1); PG8_BAR; PG8_SCHED;
;             PG8_LDB(B0, 1, 0); PG8_LDB(B1, 1, 1); PG8_SCHED; PG8_LDA(At, 1, 0); PG8_STAGE(PG8_SA(0, 1), a2 + hstep, voffA);
;             PG8_WAIT_V(8); PG8_WAIT_L(0); PG8_BAR; PG8_MMA(0, 0, At, B0); PG8_MMA(0, 1, At, B1); PG8_BAR; PG8_SCHED;
	s_setprio 1
	s_waitcnt lgkmcnt(0)
	v_mfma_f32_16x16x32_bf16 v[64:67], v[132:135], v[190:193], v[64:67]
	v_mfma_f32_16x16x32_bf16 v[60:63], v[140:143], v[190:193], v[60:63]
	v_mfma_f32_16x16x32_bf16 v[48:51], v[132:135], v[210:213], v[48:51]
	v_mfma_f32_16x16x32_bf16 v[44:47], v[140:143], v[210:213], v[44:47]
	v_mfma_f32_16x16x32_bf16 v[32:35], v[132:135], v[224:227], v[32:35]
	v_mfma_f32_16x16x32_bf16 v[28:31], v[140:143], v[224:227], v[28:31]
	v_mfma_f32_16x16x32_bf16 v[16:19], v[132:135], v[232:235], v[16:19]
	v_mfma_f32_16x16x32_bf16 v[12:15], v[140:143], v[232:235], v[12:15]
	v_mfma_f32_16x16x32_bf16 v[64:67], v[136:139], v[194:197], v[64:67]
	v_mfma_f32_16x16x32_bf16 v[60:63], v[144:147], v[194:197], v[60:63]
	v_mfma_f32_16x16x32_bf16 v[48:51], v[136:139], v[214:217], v[48:51]
	v_mfma_f32_16x16x32_bf16 v[44:47], v[144:147], v[214:217], v[44:47]
	v_mfma_f32_16x16x32_bf16 v[32:35], v[136:139], v[228:231], v[32:35]
	v_mfma_f32_16x16x32_bf16 v[28:31], v[144:147], v[228:231], v[28:31]
	v_mfma_f32_16x16x32_bf16 v[16:19], v[136:139], v[236:239], v[16:19]
	v_mfma_f32_16x16x32_bf16 v[12:15], v[144:147], v[236:239], v[12:15]
	v_mfma_f32_16x16x32_bf16 v[56:59], v[148:151], v[190:193], v[56:59]
	v_mfma_f32_16x16x32_bf16 v[52:55], v[156:159], v[190:193], v[52:55]
	v_mfma_f32_16x16x32_bf16 v[40:43], v[148:151], v[210:213], v[40:43]
	v_mfma_f32_16x16x32_bf16 v[36:39], v[156:159], v[210:213], v[36:39]
	v_mfma_f32_16x16x32_bf16 v[24:27], v[148:151], v[224:227], v[24:27]
	v_mfma_f32_16x16x32_bf16 v[20:23], v[156:159], v[224:227], v[20:23]
	v_mfma_f32_16x16x32_bf16 v[8:11], v[148:151], v[232:235], v[8:11]
	v_mfma_f32_16x16x32_bf16 v[4:7], v[156:159], v[232:235], v[4:7]
	v_mfma_f32_16x16x32_bf16 v[56:59], v[152:155], v[194:197], v[56:59]
	v_mfma_f32_16x16x32_bf16 v[52:55], v[160:163], v[194:197], v[52:55]
	v_mfma_f32_16x16x32_bf16 v[40:43], v[152:155], v[214:217], v[40:43]
	v_mfma_f32_16x16x32_bf16 v[36:39], v[160:163], v[214:217], v[36:39]
	v_mfma_f32_16x16x32_bf16 v[24:27], v[152:155], v[228:231], v[24:27]
	v_mfma_f32_16x16x32_bf16 v[20:23], v[160:163], v[228:231], v[20:23]
	v_mfma_f32_16x16x32_bf16 v[8:11], v[152:155], v[236:239], v[8:11]
	v_mfma_f32_16x16x32_bf16 v[4:7], v[160:163], v[236:239], v[4:7]
	s_setprio 0
	s_barrier
	s_add_i32 s41, 0, 0x18000
	s_add_i32 s72, 0, 0x1c000
	v_add_u32_e32 v144, s41, v168
	v_add_u32_e32 v160, s72, v168
	ds_read_b128 v[132:135], v144
	ds_read_b128 v[136:139], v144 offset:1024
	ds_read_b128 v[140:143], v144 offset:2048
	ds_read_b128 v[144:147], v144 offset:3072
	ds_read_b128 v[148:151], v160
	ds_read_b128 v[152:155], v160 offset:1024
	ds_read_b128 v[156:159], v160 offset:2048
	ds_read_b128 v[160:163], v160 offset:3072
	s_add_u32 s70, s84, 0x40000
	s_addc_u32 s71, s85, 0
	s_mov_b32 m0, s83
	v_lshl_add_u64 v[246:247], s[70:71], 0, v[184:185]
	ds_read_b128 v[190:193], v209 offset:32768
	ds_read_b128 v[194:197], v209 offset:33792
	ds_read_b128 v[210:213], v209 offset:34816
	ds_read_b128 v[214:217], v209 offset:35840
	ds_read_b128 v[224:227], v209 offset:36864
	ds_read_b128 v[228:231], v209 offset:37888
	ds_read_b128 v[232:235], v209 offset:38912
	ds_read_b128 v[236:239], v209 offset:39936
	global_load_lds_dwordx4 v[246:247], off
	v_lshl_add_u64 v[246:247], s[70:71], 0, v[182:183]
	s_mov_b32 m0, s89
	s_nop 0
	global_load_lds_dwordx4 v[246:247], off
	s_waitcnt vmcnt(8)
	s_waitcnt lgkmcnt(0)
	s_barrier
	s_setprio 1
	s_waitcnt lgkmcnt(0)
	v_mfma_f32_16x16x32_bf16 v[128:131], v[132:135], v[190:193], v[128:131]
	v_mfma_f32_16x16x32_bf16 v[124:127], v[140:143], v[190:193], v[124:127]
	v_mfma_f32_16x16x32_bf16 v[112:115], v[132:135], v[210:213], v[112:115]
	v_mfma_f32_16x16x32_bf16 v[108:111], v[140:143], v[210:213], v[108:111]
	v_mfma_f32_16x16x32_bf16 v[96:99], v[132:135], v[224:227], v[96:99]
	v_mfma_f32_16x16x32_bf16 v[92:95], v[140:143], v[224:227], v[92:95]
	v_mfma_f32_16x16x32_bf16 v[80:83], v[132:135], v[232:235], v[80:83]
	v_mfma_f32_16x16x32_bf16 v[76:79], v[140:143], v[232:235], v[76:79]
	v_mfma_f32_16x16x32_bf16 v[128:131], v[136:139], v[194:197], v[128:131]
	v_mfma_f32_16x16x32_bf16 v[124:127], v[144:147], v[194:197], v[124:127]
	v_mfma_f32_16x16x32_bf16 v[112:115], v[136:139], v[214:217], v[112:115]
	v_mfma_f32_16x16x32_bf16 v[108:111], v[144:147], v[214:217], v[108:111]
	v_mfma_f32_16x16x32_bf16 v[96:99], v[136:139], v[228:231], v[96:99]
	v_mfma_f32_16x16x32_bf16 v[92:95], v[144:147], v[228:231], v[92:95]
	v_mfma_f32_16x16x32_bf16 v[80:83], v[136:139], v[236:239], v[80:83]
	v_mfma_f32_16x16x32_bf16 v[76:79], v[144:147], v[236:239], v[76:79]
	v_mfma_f32_16x16x32_bf16 v[120:123], v[148:151], v[190:193], v[120:123]
	v_mfma_f32_16x16x32_bf16 v[116:119], v[156:159], v[190:193], v[116:119]
	v_mfma_f32_16x16x32_bf16 v[104:107], v[148:151], v[210:213], v[104:107]
	v_mfma_f32_16x16x32_bf16 v[100:103], v[156:159], v[210:213], v[100:103]
	v_mfma_f32_16x16x32_bf16 v[88:91], v[148:151], v[224:227], v[88:91]
	v_mfma_f32_16x16x32_bf16 v[84:87], v[156:159], v[224:227], v[84:87]
	v_mfma_f32_16x16x32_bf16 v[72:75], v[148:151], v[232:235], v[72:75]
	v_mfma_f32_16x16x32_bf16 v[68:71], v[156:159], v[232:235], v[68:71]
	v_mfma_f32_16x16x32_bf16 v[120:123], v[152:155], v[194:197], v[120:123]
	v_mfma_f32_16x16x32_bf16 v[116:119], v[160:163], v[194:197], v[116:119]
	v_mfma_f32_16x16x32_bf16 v[104:107], v[152:155], v[214:217], v[104:107]
	v_mfma_f32_16x16x32_bf16 v[100:103], v[160:163], v[214:217], v[100:103]
	v_mfma_f32_16x16x32_bf16 v[88:91], v[152:155], v[228:231], v[88:91]
	v_mfma_f32_16x16x32_bf16 v[84:87], v[160:163], v[228:231], v[84:87]
	v_mfma_f32_16x16x32_bf16 v[72:75], v[152:155], v[236:239], v[72:75]
	v_mfma_f32_16x16x32_bf16 v[68:71], v[160:163], v[236:239], v[68:71]
	s_setprio 0
	s_barrier
; #define PG8_STAGE(bufoff, gbase, voff) do { _Pragma("unroll") for (int _i = 0; _i < 2; ++_i) \
;         __builtin_amdgcn_global_load_lds((const unsigned*)((const char*)(gbase) + (voff)[_i]), (PG8_LAS unsigned*)(lds + (bufoff) + ldsw + _i * 8192), 16, 0, 0); } while (0)
; #define PG8_LDA(dst, b, h) do { _Pragma("unroll") for (int m = 0; m < 4; ++m) _Pragma("unroll") for (int k = 0; k < 2; ++k) dst[m][k] = *(const PG8_LAS bf16x8*)(lds + PG8_SA(b, h) + aoff + m * 2048 + k * 1024); } while (0)
; #define PG8_MMA(ai, bj, At, Bt) do { __builtin_amdgcn_s_setprio(1); _Pragma("unroll") for (int m = 0; m < 4; ++m) _Pragma("unroll") for (int n = 0; n < 2; ++n) _Pragma("unroll") for (int k = 0; k < 2; ++k) \
;         acc[ai][bj][m][n] = __builtin_amdgcn_mfma_f32_16x16x32_bf16(Bt[n][k], At[m][k], acc[ai][bj][m][n], 0, 0, 0); __builtin_amdgcn_s_setprio(0); } while (0)
; #define PG8_WAIT_V(n) asm volatile("s_waitcnt vmcnt(" #n ")" ::: "memory")
; #define PG8_WAIT_L(n) asm volatile("s_waitcnt lgkmcnt(" #n ")" ::: "memory")
; #define PG8_BAR __builtin_amdgcn_s_barrier()
; #define PG8_SCHED __builtin_amdgcn_sched_barrier(0)
; template <class Epi, class Sched, bool ALIGN_EPI = false, bool SP2 = false>
; __device__ __forceinline__ void gemm_phase(PG8_LAS unsigned char* lds, const Gemm g, const Sched& S, const Epi& E) {
;     ...
;             PG8_LDA(At, 1, 1); PG8_STAGE(PG8_SB(1, 0), b3, voffB); PG8_STAGE(PG8_SB(1, 1), b3 + hstep, voffB); PG8_STAGE(PG8_SA(1, 0), a3, voffA);
;             PG8_WAIT_V(8); PG8_WAIT_L(0); PG8_BAR; PG8_MMA(1, 0, At, B0); PG8_MMA(1, 1, At, B1); PG8_BAR; PG8_SCHED;
;     ...
;         if constexpr (ALIGN_EPI) { if (wr == 0) PG8_BAR; }
	s_add_i32 s41, s41, s80
	v_lshl_add_u64 v[218:219], v[218:219], 0, s[14:15]
	s_mov_b32 m0, s41
	ds_read_b128 v[190:193], v209 offset:49152
	ds_read_b128 v[194:197], v209 offset:50176
	ds_read_b128 v[210:213], v209 offset:51200
	ds_read_b128 v[214:217], v209 offset:52224
	ds_read_b128 v[224:227], v209 offset:53248
	ds_read_b128 v[228:231], v209 offset:54272
	ds_read_b128 v[232:235], v209 offset:55296
	ds_read_b128 v[236:239], v209 offset:56320
	global_load_lds_dwordx4 v[218:219], off
	s_add_i32 m0, s41, 0x2000
	s_add_u32 s70, s78, 0x40080
	v_lshl_add_u64 v[218:219], v[240:241], 0, s[14:15]
	s_addc_u32 s71, s79, 0
	s_add_i32 s41, s72, s80
	global_load_lds_dwordx4 v[218:219], off
	v_lshl_add_u64 v[218:219], s[70:71], 0, v[2:3]
	s_mov_b32 m0, s41
	s_nop 0
	global_load_lds_dwordx4 v[218:219], off
	v_lshl_add_u64 v[218:219], s[70:71], 0, v[180:181]
	s_add_i32 m0, s41, 0x2000
	s_nop 0
	global_load_lds_dwordx4 v[218:219], off
	v_lshl_add_u64 v[218:219], v[242:243], 0, s[14:15]
	s_mov_b32 m0, s28
	s_nop 0
	global_load_lds_dwordx4 v[218:219], off
	v_lshl_add_u64 v[218:219], v[244:245], 0, s[14:15]
	s_mov_b32 m0, s29
	s_nop 0
	global_load_lds_dwordx4 v[218:219], off
	s_waitcnt vmcnt(8)
	s_waitcnt lgkmcnt(0)
	s_barrier
	s_setprio 1
	s_waitcnt lgkmcnt(0)
	v_mfma_f32_16x16x32_bf16 v[64:67], v[132:135], v[190:193], v[64:67]
	v_mfma_f32_16x16x32_bf16 v[60:63], v[140:143], v[190:193], v[60:63]
	v_mfma_f32_16x16x32_bf16 v[48:51], v[132:135], v[210:213], v[48:51]
	v_mfma_f32_16x16x32_bf16 v[44:47], v[140:143], v[210:213], v[44:47]
	v_mfma_f32_16x16x32_bf16 v[32:35], v[132:135], v[224:227], v[32:35]
	v_mfma_f32_16x16x32_bf16 v[28:31], v[140:143], v[224:227], v[28:31]
	v_mfma_f32_16x16x32_bf16 v[16:19], v[132:135], v[232:235], v[16:19]
	v_mfma_f32_16x16x32_bf16 v[12:15], v[140:143], v[232:235], v[12:15]
	v_mfma_f32_16x16x32_bf16 v[64:67], v[136:139], v[194:197], v[64:67]
	v_mfma_f32_16x16x32_bf16 v[60:63], v[144:147], v[194:197], v[60:63]
	v_mfma_f32_16x16x32_bf16 v[48:51], v[136:139], v[214:217], v[48:51]
	v_mfma_f32_16x16x32_bf16 v[44:47], v[144:147], v[214:217], v[44:47]
	v_mfma_f32_16x16x32_bf16 v[32:35], v[136:139], v[228:231], v[32:35]
	v_mfma_f32_16x16x32_bf16 v[28:31], v[144:147], v[228:231], v[28:31]
	v_mfma_f32_16x16x32_bf16 v[16:19], v[136:139], v[236:239], v[16:19]
	v_mfma_f32_16x16x32_bf16 v[12:15], v[144:147], v[236:239], v[12:15]
	v_mfma_f32_16x16x32_bf16 v[56:59], v[148:151], v[190:193], v[56:59]
	v_mfma_f32_16x16x32_bf16 v[52:55], v[156:159], v[190:193], v[52:55]
	v_mfma_f32_16x16x32_bf16 v[40:43], v[148:151], v[210:213], v[40:43]
	v_mfma_f32_16x16x32_bf16 v[36:39], v[156:159], v[210:213], v[36:39]
	v_mfma_f32_16x16x32_bf16 v[24:27], v[148:151], v[224:227], v[24:27]
	v_mfma_f32_16x16x32_bf16 v[20:23], v[156:159], v[224:227], v[20:23]
	v_mfma_f32_16x16x32_bf16 v[8:11], v[148:151], v[232:235], v[8:11]
	v_mfma_f32_16x16x32_bf16 v[4:7], v[156:159], v[232:235], v[4:7]
	v_mfma_f32_16x16x32_bf16 v[56:59], v[152:155], v[194:197], v[56:59]
	v_mfma_f32_16x16x32_bf16 v[52:55], v[160:163], v[194:197], v[52:55]
	v_mfma_f32_16x16x32_bf16 v[40:43], v[152:155], v[214:217], v[40:43]
	v_mfma_f32_16x16x32_bf16 v[36:39], v[160:163], v[214:217], v[36:39]
	v_mfma_f32_16x16x32_bf16 v[24:27], v[152:155], v[228:231], v[24:27]
	v_mfma_f32_16x16x32_bf16 v[20:23], v[160:163], v[228:231], v[20:23]
	v_mfma_f32_16x16x32_bf16 v[8:11], v[152:155], v[236:239], v[8:11]
	v_mfma_f32_16x16x32_bf16 v[4:7], v[160:163], v[236:239], v[4:7]
	s_setprio 0
	s_add_i32 s40, s40, 2
	s_add_u32 s60, s60, 0x100
	s_addc_u32 s61, s61, 0
	s_add_u32 vcc_lo, vcc_lo, 0x100
	s_addc_u32 vcc_hi, vcc_hi, 0
	s_cmp_gt_u32 s40, 13
	s_barrier
	s_cbranch_scc0 .LBB0_790
	s_and_b64 vcc, exec, s[46:47]
	s_cbranch_vccz .LBB0_793
	s_barrier

; #define PG8_STAGE(bufoff, gbase, voff) do { _Pragma("unroll") for (int _i = 0; _i < 2; ++_i) \
;         __builtin_amdgcn_global_load_lds((const unsigned*)((const char*)(gbase) + (voff)[_i]), (PG8_LAS unsigned*)(lds + (bufoff) + ldsw + _i * 8192), 16, 0, 0); } while (0)
; #define PG8_LDA(dst, b, h) do { _Pragma("unroll") for (int m = 0; m < 4; ++m) _Pragma("unroll") for (int k = 0; k < 2; ++k) dst[m][k] = *(const PG8_LAS bf16x8*)(lds + PG8_SA(b, h) + aoff + m * 2048 + k * 1024); } while (0)
; #define PG8_LDB(dst, b, h) do { _Pragma("unroll") for (int n = 0; n < 2; ++n) _Pragma("unroll") for (int k = 0; k < 2; ++k) dst[n][k] = *(const PG8_LAS bf16x8*)(lds + PG8_SB(b, h) + boff + n * 2048 + k * 1024); } while (0)
; #define PG8_MMA(ai, bj, At, Bt) do { __builtin_amdgcn_s_setprio(1); _Pragma("unroll") for (int m = 0; m < 4; ++m) _Pragma("unroll") for (int n = 0; n < 2; ++n) _Pragma("unroll") for (int k = 0; k < 2; ++k) \
;         acc[ai][bj][m][n] = __builtin_amdgcn_mfma_f32_16x16x32_bf16(Bt[n][k], At[m][k], acc[ai][bj][m][n], 0, 0, 0); __builtin_amdgcn_s_setprio(0); } while (0)
; #define PG8_WAIT_V(n) asm volatile("s_waitcnt vmcnt(" #n ")" ::: "memory")
; #define PG8_WAIT_L(n) asm volatile("s_waitcnt lgkmcnt(" #n ")" ::: "memory")
; template <class Epi, class Sched, bool ALIGN_EPI = false, bool SP2 = false>
; __device__ __forceinline__ void gemm_phase(PG8_LAS unsigned char* lds, const Gemm g, const Sched& S, const Epi& E) {
;     ...
;             const bool last = (t == nt - 2);
;             const char* a1 = cA + (size_t)(t + 1) * kstep;
;             const char* a2 = last ? nA : cA + (size_t)(t + 2) * kstep; const char* b2 = last ? nB : cB + (size_t)(t + 2) * kstep;
;             const char* a3 = a2 + kstep; const char* b3 = b2 + kstep;
;             if (last && has_next) S.a_ready(nxt);
;             if constexpr (SP2) {
;             PG8_LDB(B0, 0, 0); PG8_LDB(B1, 0, 1); PG8_SCHED; PG8_LDA(At, 0, 0); PG8_STAGE(PG8_SA(1, 1), a1 + hstep, voffA);
;             PG8_WAIT_V(8); PG8_WAIT_L(0); PG8_BAR; PG8_MMA(0, 0, At, B0); PG8_MMA(0, 1, At, B1); PG8_BAR; PG8_SCHED;
;             PG8_LDA(At, 0, 1); PG8_STAGE(PG8_SB(0, 0), b2, voffB); PG8_STAGE(PG8_SB(0, 1), b2 + hstep, voffB); PG8_STAGE(PG8_SA(0, 0), a2, voffA);
;             PG8_WAIT_V(8); PG8_WAIT_L(0); PG8_BAR; PG8_MMA(1, 0, At, B0); PG8_MMA(1, 1, At, B1); PG8_BAR; PG8_SCHED;
.LBB0_866:
	s_add_u32 s54, s52, 0xfffc0080
	s_addc_u32 s55, s53, -1
	s_add_i32 s70, 0, 0x10000
	s_cmp_eq_u32 s89, 12
	s_cselect_b32 s61, s6, s55
	s_cselect_b32 s60, s7, s54
	v_add_u32_e32 v142, s70, v145
	s_cselect_b32 s55, s45, s85
	s_cselect_b32 s54, s47, s84
	s_add_i32 s72, 0, 0x14000
	ds_read_b128 v[148:151], v142
	ds_read_b128 v[152:155], v142 offset:1024
	ds_read_b128 v[156:159], v142 offset:2048
	ds_read_b128 v[160:163], v142 offset:3072
	v_add_u32_e32 v142, s72, v145
	ds_read_b128 v[180:183], v142
	ds_read_b128 v[184:187], v142 offset:1024
	ds_read_b128 v[188:191], v142 offset:2048
	ds_read_b128 v[192:195], v142 offset:3072
	v_lshl_add_u64 v[142:143], s[52:53], 0, v[138:139]
	s_add_i32 m0, s57, 0xc000
	ds_read_b128 v[208:211], v147
	ds_read_b128 v[212:215], v147 offset:1024
	ds_read_b128 v[216:219], v147 offset:2048
	ds_read_b128 v[224:227], v147 offset:3072
	ds_read_b128 v[228:231], v147 offset:4096
	ds_read_b128 v[232:235], v147 offset:5120
	ds_read_b128 v[236:239], v147 offset:6144
	ds_read_b128 v[240:243], v147 offset:7168
	global_load_lds_dwordx4 v[142:143], off
	v_lshl_add_u64 v[142:143], s[52:53], 0, v[140:141]
	s_add_i32 m0, s57, 0xe000
	s_nop 0
	global_load_lds_dwordx4 v[142:143], off
	s_waitcnt vmcnt(8)
	s_waitcnt lgkmcnt(0)
	s_barrier
	s_setprio 1
	s_waitcnt lgkmcnt(0)
	v_mfma_f32_16x16x32_bf16 v[128:131], v[148:151], v[208:211], v[128:131]
	v_mfma_f32_16x16x32_bf16 v[124:127], v[156:159], v[208:211], v[124:127]
	v_mfma_f32_16x16x32_bf16 v[120:123], v[148:151], v[216:219], v[120:123]
	v_mfma_f32_16x16x32_bf16 v[112:115], v[156:159], v[216:219], v[112:115]
	v_mfma_f32_16x16x32_bf16 v[104:107], v[148:151], v[228:231], v[104:107]
	v_mfma_f32_16x16x32_bf16 v[96:99], v[156:159], v[228:231], v[96:99]
	v_mfma_f32_16x16x32_bf16 v[88:91], v[148:151], v[236:239], v[88:91]
	v_mfma_f32_16x16x32_bf16 v[80:83], v[156:159], v[236:239], v[80:83]
	v_mfma_f32_16x16x32_bf16 v[128:131], v[152:155], v[212:215], v[128:131]
	v_mfma_f32_16x16x32_bf16 v[124:127], v[160:163], v[212:215], v[124:127]
	v_mfma_f32_16x16x32_bf16 v[120:123], v[152:155], v[224:227], v[120:123]
	v_mfma_f32_16x16x32_bf16 v[112:115], v[160:163], v[224:227], v[112:115]
	v_mfma_f32_16x16x32_bf16 v[104:107], v[152:155], v[232:235], v[104:107]
	v_mfma_f32_16x16x32_bf16 v[96:99], v[160:163], v[232:235], v[96:99]
	v_mfma_f32_16x16x32_bf16 v[88:91], v[152:155], v[240:243], v[88:91]
	v_mfma_f32_16x16x32_bf16 v[80:83], v[160:163], v[240:243], v[80:83]
	v_mfma_f32_16x16x32_bf16 v[116:119], v[180:183], v[208:211], v[116:119]
	v_mfma_f32_16x16x32_bf16 v[108:111], v[188:191], v[208:211], v[108:111]
	v_mfma_f32_16x16x32_bf16 v[100:103], v[180:183], v[216:219], v[100:103]
	v_mfma_f32_16x16x32_bf16 v[92:95], v[188:191], v[216:219], v[92:95]
	v_mfma_f32_16x16x32_bf16 v[84:87], v[180:183], v[228:231], v[84:87]
	v_mfma_f32_16x16x32_bf16 v[76:79], v[188:191], v[228:231], v[76:79]
	v_mfma_f32_16x16x32_bf16 v[72:75], v[180:183], v[236:239], v[72:75]
	v_mfma_f32_16x16x32_bf16 v[68:71], v[188:191], v[236:239], v[68:71]
	v_mfma_f32_16x16x32_bf16 v[116:119], v[184:187], v[212:215], v[116:119]
	v_mfma_f32_16x16x32_bf16 v[108:111], v[192:195], v[212:215], v[108:111]
	v_mfma_f32_16x16x32_bf16 v[100:103], v[184:187], v[224:227], v[100:103]
	v_mfma_f32_16x16x32_bf16 v[92:95], v[192:195], v[224:227], v[92:95]
	v_mfma_f32_16x16x32_bf16 v[84:87], v[184:187], v[232:235], v[84:87]
	v_mfma_f32_16x16x32_bf16 v[76:79], v[192:195], v[232:235], v[76:79]
	v_mfma_f32_16x16x32_bf16 v[72:75], v[184:187], v[240:243], v[72:75]
	v_mfma_f32_16x16x32_bf16 v[68:71], v[192:195], v[240:243], v[68:71]
	s_setprio 0
	s_barrier
	s_add_i32 s70, s70, s26
	v_lshl_add_u64 v[142:143], s[54:55], 0, v[2:3]
	s_mov_b32 m0, s70
	ds_read_b128 v[208:211], v147 offset:16384
	ds_read_b128 v[212:215], v147 offset:17408
	ds_read_b128 v[216:219], v147 offset:18432
	ds_read_b128 v[224:227], v147 offset:19456
	ds_read_b128 v[228:231], v147 offset:20480
	ds_read_b128 v[232:235], v147 offset:21504
	ds_read_b128 v[236:239], v147 offset:22528
	ds_read_b128 v[240:243], v147 offset:23552
	global_load_lds_dwordx4 v[142:143], off
	s_add_i32 m0, s70, 0x2000
	s_add_u32 s70, s54, 0x40000
	v_lshl_add_u64 v[170:171], s[54:55], 0, v[132:133]
	s_addc_u32 s71, s55, 0
	s_add_i32 s72, s72, s26
	global_load_lds_dwordx4 v[170:171], off
	v_lshl_add_u64 v[196:197], s[70:71], 0, v[2:3]
	s_mov_b32 m0, s72
	v_lshl_add_u64 v[244:245], s[60:61], 0, v[134:135]
	global_load_lds_dwordx4 v[196:197], off
	v_lshl_add_u64 v[196:197], s[70:71], 0, v[132:133]
	s_add_i32 m0, s72, 0x2000
	s_nop 0
	global_load_lds_dwordx4 v[196:197], off
	v_lshl_add_u64 v[196:197], s[60:61], 0, v[136:137]
	s_mov_b32 m0, s57
	s_nop 0
	global_load_lds_dwordx4 v[196:197], off
	s_mov_b32 m0, s66
	s_nop 0
	global_load_lds_dwordx4 v[244:245], off
	s_waitcnt vmcnt(8)
	s_waitcnt lgkmcnt(0)
	s_barrier
; #define PG8_STAGE(bufoff, gbase, voff) do { _Pragma("unroll") for (int _i = 0; _i < 2; ++_i) \
;         __builtin_amdgcn_global_load_lds((const unsigned*)((const char*)(gbase) + (voff)[_i]), (PG8_LAS unsigned*)(lds + (bufoff) + ldsw + _i * 8192), 16, 0, 0); } while (0)
; #define PG8_LDA(dst, b, h) do { _Pragma("unroll") for (int m = 0; m < 4; ++m) _Pragma("unroll") for (int k = 0; k < 2; ++k) dst[m][k] = *(const PG8_LAS bf16x8*)(lds + PG8_SA(b, h) + aoff + m * 2048 + k * 1024); } while (0)
; #define PG8_LDB(dst, b, h) do { _Pragma("unroll") for (int n = 0; n < 2; ++n) _Pragma("unroll") for (int k = 0; k < 2; ++k) dst[n][k] = *(const PG8_LAS bf16x8*)(lds + PG8_SB(b, h) + boff + n * 2048 + k * 1024); } while (0)
; #define PG8_MMA(ai, bj, At, Bt) do { __builtin_amdgcn_s_setprio(1); _Pragma("unroll") for (int m = 0; m < 4; ++m) _Pragma("unroll") for (int n = 0; n < 2; ++n) _Pragma("unroll") for (int k = 0; k < 2; ++k) \
;         acc[ai][bj][m][n] = __builtin_amdgcn_mfma_f32_16x16x32_bf16(Bt[n][k], At[m][k], acc[ai][bj][m][n], 0, 0, 0); __builtin_amdgcn_s_setprio(0); } while (0)
; #define PG8_WAIT_V(n) asm volatile("s_waitcnt vmcnt(" #n ")" ::: "memory")
; #define PG8_WAIT_L(n) asm volatile("s_waitcnt lgkmcnt(" #n ")" ::: "memory")
; #define PG8_BAR __builtin_amdgcn_s_barrier()
; #define PG8_SCHED __builtin_amdgcn_sched_barrier(0)
; template <class Epi, class Sched, bool ALIGN_EPI = false, bool SP2 = false>
; __device__ __forceinline__ void gemm_phase(PG8_LAS unsigned char* lds, const Gemm g, const Sched& S, const Epi& E) {
;     ...
;             PG8_WAIT_V(8); PG8_WAIT_L(0); PG8_BAR; PG8_MMA(1, 0, At, B0); PG8_MMA(1, 1, At, B1); PG8_BAR; PG8_SCHED;
;             PG8_LDB(B0, 1, 0); PG8_LDB(B1, 1, 1); PG8_SCHED; PG8_LDA(At, 1, 0); PG8_STAGE(PG8_SA(0, 1), a2 + hstep, voffA);
;             PG8_WAIT_V(8); PG8_WAIT_L(0); PG8_BAR; PG8_MMA(0, 0, At, B0); PG8_MMA(0, 1, At, B1); PG8_BAR; PG8_SCHED;
	s_setprio 1
	s_waitcnt lgkmcnt(0)
	v_mfma_f32_16x16x32_bf16 v[64:67], v[148:151], v[208:211], v[64:67]
	v_mfma_f32_16x16x32_bf16 v[60:63], v[156:159], v[208:211], v[60:63]
	v_mfma_f32_16x16x32_bf16 v[56:59], v[148:151], v[216:219], v[56:59]
	v_mfma_f32_16x16x32_bf16 v[48:51], v[156:159], v[216:219], v[48:51]
	v_mfma_f32_16x16x32_bf16 v[40:43], v[148:151], v[228:231], v[40:43]
	v_mfma_f32_16x16x32_bf16 v[32:35], v[156:159], v[228:231], v[32:35]
	v_mfma_f32_16x16x32_bf16 v[24:27], v[148:151], v[236:239], v[24:27]
	v_mfma_f32_16x16x32_bf16 v[16:19], v[156:159], v[236:239], v[16:19]
	v_mfma_f32_16x16x32_bf16 v[64:67], v[152:155], v[212:215], v[64:67]
	v_mfma_f32_16x16x32_bf16 v[60:63], v[160:163], v[212:215], v[60:63]
	v_mfma_f32_16x16x32_bf16 v[56:59], v[152:155], v[224:227], v[56:59]
	v_mfma_f32_16x16x32_bf16 v[48:51], v[160:163], v[224:227], v[48:51]
	v_mfma_f32_16x16x32_bf16 v[40:43], v[152:155], v[232:235], v[40:43]
	v_mfma_f32_16x16x32_bf16 v[32:35], v[160:163], v[232:235], v[32:35]
	v_mfma_f32_16x16x32_bf16 v[24:27], v[152:155], v[240:243], v[24:27]
	v_mfma_f32_16x16x32_bf16 v[16:19], v[160:163], v[240:243], v[16:19]
	v_mfma_f32_16x16x32_bf16 v[52:55], v[180:183], v[208:211], v[52:55]
	v_mfma_f32_16x16x32_bf16 v[44:47], v[188:191], v[208:211], v[44:47]
	v_mfma_f32_16x16x32_bf16 v[36:39], v[180:183], v[216:219], v[36:39]
	v_mfma_f32_16x16x32_bf16 v[28:31], v[188:191], v[216:219], v[28:31]
	v_mfma_f32_16x16x32_bf16 v[20:23], v[180:183], v[228:231], v[20:23]
	v_mfma_f32_16x16x32_bf16 v[12:15], v[188:191], v[228:231], v[12:15]
	v_mfma_f32_16x16x32_bf16 v[8:11], v[180:183], v[236:239], v[8:11]
	v_mfma_f32_16x16x32_bf16 v[4:7], v[188:191], v[236:239], v[4:7]
	v_mfma_f32_16x16x32_bf16 v[52:55], v[184:187], v[212:215], v[52:55]
	v_mfma_f32_16x16x32_bf16 v[44:47], v[192:195], v[212:215], v[44:47]
	v_mfma_f32_16x16x32_bf16 v[36:39], v[184:187], v[224:227], v[36:39]
	v_mfma_f32_16x16x32_bf16 v[28:31], v[192:195], v[224:227], v[28:31]
	v_mfma_f32_16x16x32_bf16 v[20:23], v[184:187], v[232:235], v[20:23]
	v_mfma_f32_16x16x32_bf16 v[12:15], v[192:195], v[232:235], v[12:15]
	v_mfma_f32_16x16x32_bf16 v[8:11], v[184:187], v[240:243], v[8:11]
	v_mfma_f32_16x16x32_bf16 v[4:7], v[192:195], v[240:243], v[4:7]
	s_setprio 0
	s_barrier
	s_add_i32 s70, 0, 0x18000
	s_add_i32 s71, 0, 0x1c000
	v_add_u32_e32 v160, s70, v145
	v_add_u32_e32 v167, s71, v145
	ds_read_b128 v[148:151], v160
	ds_read_b128 v[152:155], v160 offset:1024
	ds_read_b128 v[156:159], v160 offset:2048
	ds_read_b128 v[160:163], v160 offset:3072
	ds_read_b128 v[180:183], v167
	ds_read_b128 v[184:187], v167 offset:1024
	ds_read_b128 v[188:191], v167 offset:2048
	ds_read_b128 v[192:195], v167 offset:3072
	s_add_u32 s60, s60, 0x40000
	s_addc_u32 s61, s61, 0
	s_mov_b32 m0, s67
	v_lshl_add_u64 v[246:247], s[60:61], 0, v[136:137]
	ds_read_b128 v[208:211], v147 offset:32768
	ds_read_b128 v[212:215], v147 offset:33792
	ds_read_b128 v[216:219], v147 offset:34816
	ds_read_b128 v[224:227], v147 offset:35840
	ds_read_b128 v[228:231], v147 offset:36864
	ds_read_b128 v[232:235], v147 offset:37888
	ds_read_b128 v[236:239], v147 offset:38912
	ds_read_b128 v[240:243], v147 offset:39936
	global_load_lds_dwordx4 v[246:247], off
	v_lshl_add_u64 v[246:247], s[60:61], 0, v[134:135]
	s_mov_b32 m0, s78
	s_nop 0
	global_load_lds_dwordx4 v[246:247], off
	s_waitcnt vmcnt(8)
	s_waitcnt lgkmcnt(0)
	s_barrier
	s_setprio 1
	s_waitcnt lgkmcnt(0)
	v_mfma_f32_16x16x32_bf16 v[128:131], v[148:151], v[208:211], v[128:131]
	v_mfma_f32_16x16x32_bf16 v[124:127], v[156:159], v[208:211], v[124:127]
	v_mfma_f32_16x16x32_bf16 v[120:123], v[148:151], v[216:219], v[120:123]
	v_mfma_f32_16x16x32_bf16 v[112:115], v[156:159], v[216:219], v[112:115]
	v_mfma_f32_16x16x32_bf16 v[104:107], v[148:151], v[228:231], v[104:107]
	v_mfma_f32_16x16x32_bf16 v[96:99], v[156:159], v[228:231], v[96:99]
	v_mfma_f32_16x16x32_bf16 v[88:91], v[148:151], v[236:239], v[88:91]
	v_mfma_f32_16x16x32_bf16 v[80:83], v[156:159], v[236:239], v[80:83]
	v_mfma_f32_16x16x32_bf16 v[128:131], v[152:155], v[212:215], v[128:131]
	v_mfma_f32_16x16x32_bf16 v[124:127], v[160:163], v[212:215], v[124:127]
	v_mfma_f32_16x16x32_bf16 v[120:123], v[152:155], v[224:227], v[120:123]
	v_mfma_f32_16x16x32_bf16 v[112:115], v[160:163], v[224:227], v[112:115]
	v_mfma_f32_16x16x32_bf16 v[104:107], v[152:155], v[232:235], v[104:107]
	v_mfma_f32_16x16x32_bf16 v[96:99], v[160:163], v[232:235], v[96:99]
	v_mfma_f32_16x16x32_bf16 v[88:91], v[152:155], v[240:243], v[88:91]
	v_mfma_f32_16x16x32_bf16 v[80:83], v[160:163], v[240:243], v[80:83]
	v_mfma_f32_16x16x32_bf16 v[116:119], v[180:183], v[208:211], v[116:119]
	v_mfma_f32_16x16x32_bf16 v[108:111], v[188:191], v[208:211], v[108:111]
	v_mfma_f32_16x16x32_bf16 v[100:103], v[180:183], v[216:219], v[100:103]
	v_mfma_f32_16x16x32_bf16 v[92:95], v[188:191], v[216:219], v[92:95]
	v_mfma_f32_16x16x32_bf16 v[84:87], v[180:183], v[228:231], v[84:87]
	v_mfma_f32_16x16x32_bf16 v[76:79], v[188:191], v[228:231], v[76:79]
	v_mfma_f32_16x16x32_bf16 v[72:75], v[180:183], v[236:239], v[72:75]
	v_mfma_f32_16x16x32_bf16 v[68:71], v[188:191], v[236:239], v[68:71]
	v_mfma_f32_16x16x32_bf16 v[116:119], v[184:187], v[212:215], v[116:119]
	v_mfma_f32_16x16x32_bf16 v[108:111], v[192:195], v[212:215], v[108:111]
	v_mfma_f32_16x16x32_bf16 v[100:103], v[184:187], v[224:227], v[100:103]
	v_mfma_f32_16x16x32_bf16 v[92:95], v[192:195], v[224:227], v[92:95]
	v_mfma_f32_16x16x32_bf16 v[84:87], v[184:187], v[232:235], v[84:87]
	v_mfma_f32_16x16x32_bf16 v[76:79], v[192:195], v[232:235], v[76:79]
	v_mfma_f32_16x16x32_bf16 v[72:75], v[184:187], v[240:243], v[72:75]
	v_mfma_f32_16x16x32_bf16 v[68:71], v[192:195], v[240:243], v[68:71]
	s_setprio 0
	s_barrier
; #define PG8_STAGE(bufoff, gbase, voff) do { _Pragma("unroll") for (int _i = 0; _i < 2; ++_i) \
;         __builtin_amdgcn_global_load_lds((const unsigned*)((const char*)(gbase) + (voff)[_i]), (PG8_LAS unsigned*)(lds + (bufoff) + ldsw + _i * 8192), 16, 0, 0); } while (0)
; #define PG8_LDA(dst, b, h) do { _Pragma("unroll") for (int m = 0; m < 4; ++m) _Pragma("unroll") for (int k = 0; k < 2; ++k) dst[m][k] = *(const PG8_LAS bf16x8*)(lds + PG8_SA(b, h) + aoff + m * 2048 + k * 1024); } while (0)
; #define PG8_MMA(ai, bj, At, Bt) do { __builtin_amdgcn_s_setprio(1); _Pragma("unroll") for (int m = 0; m < 4; ++m) _Pragma("unroll") for (int n = 0; n < 2; ++n) _Pragma("unroll") for (int k = 0; k < 2; ++k) \
;         acc[ai][bj][m][n] = __builtin_amdgcn_mfma_f32_16x16x32_bf16(Bt[n][k], At[m][k], acc[ai][bj][m][n], 0, 0, 0); __builtin_amdgcn_s_setprio(0); } while (0)
; #define PG8_WAIT_V(n) asm volatile("s_waitcnt vmcnt(" #n ")" ::: "memory")
; #define PG8_WAIT_L(n) asm volatile("s_waitcnt lgkmcnt(" #n ")" ::: "memory")
; #define PG8_BAR __builtin_amdgcn_s_barrier()
; #define PG8_SCHED __builtin_amdgcn_sched_barrier(0)
; template <class Epi, class Sched, bool ALIGN_EPI = false, bool SP2 = false>
; __device__ __forceinline__ void gemm_phase(PG8_LAS unsigned char* lds, const Gemm g, const Sched& S, const Epi& E) {
;     ...
;             PG8_LDA(At, 1, 1); PG8_STAGE(PG8_SB(1, 0), b3, voffB); PG8_STAGE(PG8_SB(1, 1), b3 + hstep, voffB); PG8_STAGE(PG8_SA(1, 0), a3, voffA);
;             PG8_WAIT_V(8); PG8_WAIT_L(0); PG8_BAR; PG8_MMA(1, 0, At, B0); PG8_MMA(1, 1, At, B1); PG8_BAR; PG8_SCHED;
;     ...
;         if constexpr (ALIGN_EPI) { if (wr == 0) PG8_BAR; }
	s_add_i32 s60, s70, s26
	v_lshl_add_u64 v[142:143], v[142:143], 0, s[14:15]
	s_mov_b32 m0, s60
	ds_read_b128 v[208:211], v147 offset:49152
	ds_read_b128 v[212:215], v147 offset:50176
	ds_read_b128 v[216:219], v147 offset:51200
	ds_read_b128 v[224:227], v147 offset:52224
	ds_read_b128 v[228:231], v147 offset:53248
	ds_read_b128 v[232:235], v147 offset:54272
	ds_read_b128 v[236:239], v147 offset:55296
	ds_read_b128 v[240:243], v147 offset:56320
	global_load_lds_dwordx4 v[142:143], off
	s_add_i32 m0, s60, 0x2000
	s_add_u32 s54, s54, 0x40080
	v_lshl_add_u64 v[142:143], v[170:171], 0, s[14:15]
	s_addc_u32 s55, s55, 0
	s_add_i32 s60, s71, s26
	global_load_lds_dwordx4 v[142:143], off
	v_lshl_add_u64 v[142:143], s[54:55], 0, v[2:3]
	s_mov_b32 m0, s60
	s_nop 0
	global_load_lds_dwordx4 v[142:143], off
	v_lshl_add_u64 v[142:143], s[54:55], 0, v[132:133]
	s_add_i32 m0, s60, 0x2000
	s_nop 0
	global_load_lds_dwordx4 v[142:143], off
	v_lshl_add_u64 v[142:143], v[196:197], 0, s[14:15]
	s_mov_b32 m0, s79
	s_nop 0
	global_load_lds_dwordx4 v[142:143], off
	v_lshl_add_u64 v[142:143], v[244:245], 0, s[14:15]
	s_mov_b32 m0, s80
	s_nop 0
	global_load_lds_dwordx4 v[142:143], off
	s_waitcnt vmcnt(8)
	s_waitcnt lgkmcnt(0)
	s_barrier
	s_setprio 1
	s_waitcnt lgkmcnt(0)
	v_mfma_f32_16x16x32_bf16 v[64:67], v[148:151], v[208:211], v[64:67]
	v_mfma_f32_16x16x32_bf16 v[60:63], v[156:159], v[208:211], v[60:63]
	v_mfma_f32_16x16x32_bf16 v[56:59], v[148:151], v[216:219], v[56:59]
	v_mfma_f32_16x16x32_bf16 v[48:51], v[156:159], v[216:219], v[48:51]
	v_mfma_f32_16x16x32_bf16 v[40:43], v[148:151], v[228:231], v[40:43]
	v_mfma_f32_16x16x32_bf16 v[32:35], v[156:159], v[228:231], v[32:35]
	v_mfma_f32_16x16x32_bf16 v[24:27], v[148:151], v[236:239], v[24:27]
	v_mfma_f32_16x16x32_bf16 v[16:19], v[156:159], v[236:239], v[16:19]
	v_mfma_f32_16x16x32_bf16 v[64:67], v[152:155], v[212:215], v[64:67]
	v_mfma_f32_16x16x32_bf16 v[60:63], v[160:163], v[212:215], v[60:63]
	v_mfma_f32_16x16x32_bf16 v[56:59], v[152:155], v[224:227], v[56:59]
	v_mfma_f32_16x16x32_bf16 v[48:51], v[160:163], v[224:227], v[48:51]
	v_mfma_f32_16x16x32_bf16 v[40:43], v[152:155], v[232:235], v[40:43]
	v_mfma_f32_16x16x32_bf16 v[32:35], v[160:163], v[232:235], v[32:35]
	v_mfma_f32_16x16x32_bf16 v[24:27], v[152:155], v[240:243], v[24:27]
	v_mfma_f32_16x16x32_bf16 v[16:19], v[160:163], v[240:243], v[16:19]
	v_mfma_f32_16x16x32_bf16 v[52:55], v[180:183], v[208:211], v[52:55]
	v_mfma_f32_16x16x32_bf16 v[44:47], v[188:191], v[208:211], v[44:47]
	v_mfma_f32_16x16x32_bf16 v[36:39], v[180:183], v[216:219], v[36:39]
	v_mfma_f32_16x16x32_bf16 v[28:31], v[188:191], v[216:219], v[28:31]
	v_mfma_f32_16x16x32_bf16 v[20:23], v[180:183], v[228:231], v[20:23]
	v_mfma_f32_16x16x32_bf16 v[12:15], v[188:191], v[228:231], v[12:15]
	v_mfma_f32_16x16x32_bf16 v[8:11], v[180:183], v[236:239], v[8:11]
	v_mfma_f32_16x16x32_bf16 v[4:7], v[188:191], v[236:239], v[4:7]
	v_mfma_f32_16x16x32_bf16 v[52:55], v[184:187], v[212:215], v[52:55]
	v_mfma_f32_16x16x32_bf16 v[44:47], v[192:195], v[212:215], v[44:47]
	v_mfma_f32_16x16x32_bf16 v[36:39], v[184:187], v[224:227], v[36:39]
	v_mfma_f32_16x16x32_bf16 v[28:31], v[192:195], v[224:227], v[28:31]
	v_mfma_f32_16x16x32_bf16 v[20:23], v[184:187], v[232:235], v[20:23]
	v_mfma_f32_16x16x32_bf16 v[12:15], v[192:195], v[232:235], v[12:15]
	v_mfma_f32_16x16x32_bf16 v[8:11], v[184:187], v[240:243], v[8:11]
	v_mfma_f32_16x16x32_bf16 v[4:7], v[192:195], v[240:243], v[4:7]
	s_setprio 0
	s_add_i32 s89, s89, 2
	s_add_u32 s52, s52, 0x100
	s_addc_u32 s53, s53, 0
	s_add_u32 s84, s84, 0x100
	s_addc_u32 s85, s85, 0
	s_cmp_gt_u32 s89, 13
	s_barrier
	s_cbranch_scc0 .LBB0_866
	s_and_b64 vcc, exec, s[42:43]
	s_cbranch_vccz .LBB0_869
	s_barrier
